# cache policy: ada_w reads of the prologue's modulation GEMV (100 MB read once) non-temporal
# speedup vs baseline: 1.0145x; 1.0079x over previous
; #define LAS __attribute__((address_space(3)))
; __device__ __forceinline__ void prologue(const __attribute__((address_space(4))) Args& a, ldsp lds, int gw, int NGW, int wave, int lane, const int tid, const int bid, const int G) {
;     ...
;     for (int u = bid; u < 4 * 96; u += G) {
;         const int layer = u / 96, col0 = (u % 96) * 64;
;         const float* Wl = a.ada_w + (size_t)layer * D * NMOD + col0 + lane;
;         float acc[9];
; #pragma unroll
;         for (int j = 0; j < 9; ++j) acc[j] = 0.f;
;         for (int k = wave * 128; k < wave * 128 + 128; k += 16) {
;             float wv[16];
; #pragma unroll
;             for (int q = 0; q < 16; ++q) wv[q] = Wl[(size_t)(k + q) * NMOD];
; #pragma unroll
;             for (int q4 = 0; q4 < 4; ++q4)
; #pragma unroll
;                 for (int j = 0; j < 9; ++j) { const f32x4 s4 = *(const LAS f32x4*)(sc + j * D + k + 4 * q4); acc[j] += s4[0] * wv[4 * q4] + s4[1] * wv[4 * q4 + 1] + s4[2] * wv[4 * q4 + 2] + s4[3] * wv[4 * q4 + 3]; }
.LBB0_1277:
	s_mul_hi_i32 s6, s96, 0x2aaaaaab
	s_lshr_b32 s7, s6, 31
	s_ashr_i32 s6, s6, 4
	s_add_i32 s12, s6, s7
	s_mul_i32 s6, s12, 0x60
	s_sub_i32 s6, s96, s6
	s_lshl_b32 s6, s6, 6
	s_ashr_i32 s7, s6, 31
	s_mul_i32 s14, s12, 0x1800000
	s_lshl_b64 s[8:9], s[6:7], 2
	s_mul_hi_i32 s13, s12, 0x1800000
	s_add_u32 s8, s14, s8
	s_addc_u32 s9, s13, s9
	v_mov_b32_e32 v78, 0
	v_lshl_add_u64 v[76:77], v[74:75], 0, s[8:9]
	s_mov_b32 s8, s3
	s_mov_b32 s9, s1
	v_mov_b32_e32 v79, v78
	v_mov_b32_e32 v84, v78
	v_mov_b32_e32 v85, v78
	v_mov_b32_e32 v82, v78
	v_mov_b32_e32 v83, v78
	v_mov_b32_e32 v80, v78
	v_mov_b32_e32 v81, v78
	v_mov_b32_e32 v92, v78
	v_readfirstlane_b32 s22, v76
	v_readfirstlane_b32 s23, v77
	v_lshlrev_b32_e32 v0, 2, v87
	v_mov_b32_e32 v1, s8
	s_sub_u32 s22, s22, 0x5a000
	s_subb_u32 s23, s23, 0
	s_nop 1
	global_load_dword v2, v0, s[22:23] nt
	s_add_u32 s22, s22, 0x6000
	s_addc_u32 s23, s23, 0
	global_load_dword v3, v0, s[22:23] nt
	s_add_u32 s22, s22, 0x6000
	s_addc_u32 s23, s23, 0
	global_load_dword v4, v0, s[22:23] nt
	s_add_u32 s22, s22, 0x6000
	s_addc_u32 s23, s23, 0
	global_load_dword v5, v0, s[22:23] nt
	s_add_u32 s22, s22, 0x6000
	s_addc_u32 s23, s23, 0
	global_load_dword v6, v0, s[22:23] nt
	s_add_u32 s22, s22, 0x6000
	s_addc_u32 s23, s23, 0
	global_load_dword v7, v0, s[22:23] nt
	s_add_u32 s22, s22, 0x6000
	s_addc_u32 s23, s23, 0
	global_load_dword v8, v0, s[22:23] nt
	s_add_u32 s22, s22, 0x6000
	s_addc_u32 s23, s23, 0
	global_load_dword v9, v0, s[22:23] nt
	s_add_u32 s22, s22, 0x6000
	s_addc_u32 s23, s23, 0
	global_load_dword v10, v0, s[22:23] nt
	s_add_u32 s22, s22, 0x6000
	s_addc_u32 s23, s23, 0
	global_load_dword v11, v0, s[22:23] nt
	s_add_u32 s22, s22, 0x6000
	s_addc_u32 s23, s23, 0
	global_load_dword v12, v0, s[22:23] nt
	s_add_u32 s22, s22, 0x6000
	s_addc_u32 s23, s23, 0
	global_load_dword v13, v0, s[22:23] nt
	s_add_u32 s22, s22, 0x6000
	s_addc_u32 s23, s23, 0
	global_load_dword v14, v0, s[22:23] nt
	s_add_u32 s22, s22, 0x6000
	s_addc_u32 s23, s23, 0
	global_load_dword v15, v0, s[22:23] nt
	s_add_u32 s22, s22, 0x6000
	s_addc_u32 s23, s23, 0
	global_load_dword v16, v0, s[22:23] nt
	s_add_u32 s22, s22, 0x6000
	s_addc_u32 s23, s23, 0
	global_load_dword v17, v0, s[22:23] nt
	s_add_u32 s22, s22, 0x6000
	s_addc_u32 s23, s23, 0
	ds_read_b128 v[98:101], v1 offset:0
	ds_read_b128 v[102:105], v1 offset:4096
	ds_read_b128 v[106:109], v1 offset:8192
	ds_read_b128 v[110:113], v1 offset:12288
	ds_read_b128 v[114:117], v1 offset:16384
	ds_read_b128 v[118:121], v1 offset:20480
	ds_read_b128 v[122:125], v1 offset:24576
	ds_read_b128 v[126:129], v1 offset:28672
	ds_read_b128 v[130:133], v1 offset:32768
	global_load_dword v34, v0, s[22:23] nt
	s_add_u32 s22, s22, 0x6000
	s_addc_u32 s23, s23, 0
	global_load_dword v35, v0, s[22:23] nt
	s_add_u32 s22, s22, 0x6000
	s_addc_u32 s23, s23, 0
	global_load_dword v36, v0, s[22:23] nt
	s_add_u32 s22, s22, 0x6000
	s_addc_u32 s23, s23, 0
	global_load_dword v37, v0, s[22:23] nt
	s_add_u32 s22, s22, 0x6000
	s_addc_u32 s23, s23, 0
	global_load_dword v38, v0, s[22:23] nt
	s_add_u32 s22, s22, 0x6000
	s_addc_u32 s23, s23, 0
	global_load_dword v39, v0, s[22:23] nt
	s_add_u32 s22, s22, 0x6000
	s_addc_u32 s23, s23, 0
	global_load_dword v40, v0, s[22:23] nt
	s_add_u32 s22, s22, 0x6000
	s_addc_u32 s23, s23, 0
	global_load_dword v41, v0, s[22:23] nt
	s_add_u32 s22, s22, 0x6000
	s_addc_u32 s23, s23, 0
	global_load_dword v42, v0, s[22:23] nt
	s_add_u32 s22, s22, 0x6000
	s_addc_u32 s23, s23, 0
	global_load_dword v43, v0, s[22:23] nt
	s_add_u32 s22, s22, 0x6000
	s_addc_u32 s23, s23, 0
	global_load_dword v44, v0, s[22:23] nt
	s_add_u32 s22, s22, 0x6000
	s_addc_u32 s23, s23, 0
	global_load_dword v45, v0, s[22:23] nt
	s_add_u32 s22, s22, 0x6000
	s_addc_u32 s23, s23, 0
	global_load_dword v46, v0, s[22:23] nt
	s_add_u32 s22, s22, 0x6000
	s_addc_u32 s23, s23, 0
	global_load_dword v47, v0, s[22:23] nt
	s_add_u32 s22, s22, 0x6000
	s_addc_u32 s23, s23, 0
	global_load_dword v48, v0, s[22:23] nt
	s_add_u32 s22, s22, 0x6000
	s_addc_u32 s23, s23, 0
	global_load_dword v49, v0, s[22:23] nt
	s_add_u32 s22, s22, 0x6000
	s_addc_u32 s23, s23, 0
	v_mov_b64_e32 v[226:227], 0
	v_mov_b64_e32 v[228:229], 0
	v_mov_b64_e32 v[230:231], 0
	v_mov_b64_e32 v[232:233], 0
	v_mov_b64_e32 v[234:235], 0
	v_mov_b64_e32 v[236:237], 0
	v_mov_b64_e32 v[238:239], 0
	v_mov_b64_e32 v[240:241], 0
	v_mov_b64_e32 v[242:243], 0
	s_waitcnt vmcnt(16)
	ds_read_b128 v[134:137], v1 offset:16
	ds_read_b128 v[138:141], v1 offset:4112
	ds_read_b128 v[142:145], v1 offset:8208
	ds_read_b128 v[146:149], v1 offset:12304
	ds_read_b128 v[150:153], v1 offset:16400
	ds_read_b128 v[154:157], v1 offset:20496
	ds_read_b128 v[158:161], v1 offset:24592
	ds_read_b128 v[162:165], v1 offset:28688
	ds_read_b128 v[166:169], v1 offset:32784
	s_waitcnt lgkmcnt(9)
	v_pk_fma_f32 v[226:227], v[98:99], v[2:3], v[226:227]
	v_pk_fma_f32 v[228:229], v[102:103], v[2:3], v[228:229]
	v_pk_fma_f32 v[230:231], v[106:107], v[2:3], v[230:231]
	v_pk_fma_f32 v[232:233], v[110:111], v[2:3], v[232:233]
	v_pk_fma_f32 v[234:235], v[114:115], v[2:3], v[234:235]
	v_pk_fma_f32 v[236:237], v[118:119], v[2:3], v[236:237]
	v_pk_fma_f32 v[238:239], v[122:123], v[2:3], v[238:239]
	v_pk_fma_f32 v[240:241], v[126:127], v[2:3], v[240:241]
	v_pk_fma_f32 v[242:243], v[130:131], v[2:3], v[242:243]
	v_pk_fma_f32 v[226:227], v[100:101], v[4:5], v[226:227]
	v_pk_fma_f32 v[228:229], v[104:105], v[4:5], v[228:229]
	v_pk_fma_f32 v[230:231], v[108:109], v[4:5], v[230:231]
	v_pk_fma_f32 v[232:233], v[112:113], v[4:5], v[232:233]
	v_pk_fma_f32 v[234:235], v[116:117], v[4:5], v[234:235]
	v_pk_fma_f32 v[236:237], v[120:121], v[4:5], v[236:237]
	v_pk_fma_f32 v[238:239], v[124:125], v[4:5], v[238:239]
	v_pk_fma_f32 v[240:241], v[128:129], v[4:5], v[240:241]
	v_pk_fma_f32 v[242:243], v[132:133], v[4:5], v[242:243]
	ds_read_b128 v[98:101], v1 offset:32
	ds_read_b128 v[102:105], v1 offset:4128
	ds_read_b128 v[106:109], v1 offset:8224
	ds_read_b128 v[110:113], v1 offset:12320
	ds_read_b128 v[114:117], v1 offset:16416
	ds_read_b128 v[118:121], v1 offset:20512
	ds_read_b128 v[122:125], v1 offset:24608
	ds_read_b128 v[126:129], v1 offset:28704
	ds_read_b128 v[130:133], v1 offset:32800
	s_waitcnt lgkmcnt(9)
; #define LAS __attribute__((address_space(3)))
; __device__ __forceinline__ void prologue(const __attribute__((address_space(4))) Args& a, ldsp lds, int gw, int NGW, int wave, int lane, const int tid, const int bid, const int G) {
;     ...
;         for (int k = wave * 128; k < wave * 128 + 128; k += 16) {
;             float wv[16];
; #pragma unroll
;             for (int q = 0; q < 16; ++q) wv[q] = Wl[(size_t)(k + q) * NMOD];
; #pragma unroll
;             for (int q4 = 0; q4 < 4; ++q4)
; #pragma unroll
;                 for (int j = 0; j < 9; ++j) { const f32x4 s4 = *(const LAS f32x4*)(sc + j * D + k + 4 * q4); acc[j] += s4[0] * wv[4 * q4] + s4[1] * wv[4 * q4 + 1] + s4[2] * wv[4 * q4 + 2] + s4[3] * wv[4 * q4 + 3]; }
	v_pk_fma_f32 v[226:227], v[134:135], v[6:7], v[226:227]
	v_pk_fma_f32 v[228:229], v[138:139], v[6:7], v[228:229]
	v_pk_fma_f32 v[230:231], v[142:143], v[6:7], v[230:231]
	v_pk_fma_f32 v[232:233], v[146:147], v[6:7], v[232:233]
	v_pk_fma_f32 v[234:235], v[150:151], v[6:7], v[234:235]
	v_pk_fma_f32 v[236:237], v[154:155], v[6:7], v[236:237]
	v_pk_fma_f32 v[238:239], v[158:159], v[6:7], v[238:239]
	v_pk_fma_f32 v[240:241], v[162:163], v[6:7], v[240:241]
	v_pk_fma_f32 v[242:243], v[166:167], v[6:7], v[242:243]
	v_pk_fma_f32 v[226:227], v[136:137], v[8:9], v[226:227]
	v_pk_fma_f32 v[228:229], v[140:141], v[8:9], v[228:229]
	v_pk_fma_f32 v[230:231], v[144:145], v[8:9], v[230:231]
	v_pk_fma_f32 v[232:233], v[148:149], v[8:9], v[232:233]
	v_pk_fma_f32 v[234:235], v[152:153], v[8:9], v[234:235]
	v_pk_fma_f32 v[236:237], v[156:157], v[8:9], v[236:237]
	v_pk_fma_f32 v[238:239], v[160:161], v[8:9], v[238:239]
	v_pk_fma_f32 v[240:241], v[164:165], v[8:9], v[240:241]
	v_pk_fma_f32 v[242:243], v[168:169], v[8:9], v[242:243]
	ds_read_b128 v[134:137], v1 offset:48
	ds_read_b128 v[138:141], v1 offset:4144
	ds_read_b128 v[142:145], v1 offset:8240
	ds_read_b128 v[146:149], v1 offset:12336
	ds_read_b128 v[150:153], v1 offset:16432
	ds_read_b128 v[154:157], v1 offset:20528
	ds_read_b128 v[158:161], v1 offset:24624
	ds_read_b128 v[162:165], v1 offset:28720
	ds_read_b128 v[166:169], v1 offset:32816
	s_waitcnt lgkmcnt(9)
	v_pk_fma_f32 v[226:227], v[98:99], v[10:11], v[226:227]
	v_pk_fma_f32 v[228:229], v[102:103], v[10:11], v[228:229]
	v_pk_fma_f32 v[230:231], v[106:107], v[10:11], v[230:231]
	v_pk_fma_f32 v[232:233], v[110:111], v[10:11], v[232:233]
	v_pk_fma_f32 v[234:235], v[114:115], v[10:11], v[234:235]
	v_pk_fma_f32 v[236:237], v[118:119], v[10:11], v[236:237]
	v_pk_fma_f32 v[238:239], v[122:123], v[10:11], v[238:239]
	v_pk_fma_f32 v[240:241], v[126:127], v[10:11], v[240:241]
	v_pk_fma_f32 v[242:243], v[130:131], v[10:11], v[242:243]
	v_pk_fma_f32 v[226:227], v[100:101], v[12:13], v[226:227]
	v_pk_fma_f32 v[228:229], v[104:105], v[12:13], v[228:229]
	v_pk_fma_f32 v[230:231], v[108:109], v[12:13], v[230:231]
	v_pk_fma_f32 v[232:233], v[112:113], v[12:13], v[232:233]
	v_pk_fma_f32 v[234:235], v[116:117], v[12:13], v[234:235]
	v_pk_fma_f32 v[236:237], v[120:121], v[12:13], v[236:237]
	v_pk_fma_f32 v[238:239], v[124:125], v[12:13], v[238:239]
	v_pk_fma_f32 v[240:241], v[128:129], v[12:13], v[240:241]
	v_pk_fma_f32 v[242:243], v[132:133], v[12:13], v[242:243]
	ds_read_b128 v[98:101], v1 offset:64
	ds_read_b128 v[102:105], v1 offset:4160
	ds_read_b128 v[106:109], v1 offset:8256
	ds_read_b128 v[110:113], v1 offset:12352
	ds_read_b128 v[114:117], v1 offset:16448
	ds_read_b128 v[118:121], v1 offset:20544
	ds_read_b128 v[122:125], v1 offset:24640
	ds_read_b128 v[126:129], v1 offset:28736
	ds_read_b128 v[130:133], v1 offset:32832
	s_waitcnt lgkmcnt(9)
	v_pk_fma_f32 v[226:227], v[134:135], v[14:15], v[226:227]
	v_pk_fma_f32 v[228:229], v[138:139], v[14:15], v[228:229]
	v_pk_fma_f32 v[230:231], v[142:143], v[14:15], v[230:231]
	v_pk_fma_f32 v[232:233], v[146:147], v[14:15], v[232:233]
	v_pk_fma_f32 v[234:235], v[150:151], v[14:15], v[234:235]
	v_pk_fma_f32 v[236:237], v[154:155], v[14:15], v[236:237]
	v_pk_fma_f32 v[238:239], v[158:159], v[14:15], v[238:239]
	v_pk_fma_f32 v[240:241], v[162:163], v[14:15], v[240:241]
	v_pk_fma_f32 v[242:243], v[166:167], v[14:15], v[242:243]
	v_pk_fma_f32 v[226:227], v[136:137], v[16:17], v[226:227]
	v_pk_fma_f32 v[228:229], v[140:141], v[16:17], v[228:229]
	v_pk_fma_f32 v[230:231], v[144:145], v[16:17], v[230:231]
	v_pk_fma_f32 v[232:233], v[148:149], v[16:17], v[232:233]
	v_pk_fma_f32 v[234:235], v[152:153], v[16:17], v[234:235]
	v_pk_fma_f32 v[236:237], v[156:157], v[16:17], v[236:237]
	v_pk_fma_f32 v[238:239], v[160:161], v[16:17], v[238:239]
	v_pk_fma_f32 v[240:241], v[164:165], v[16:17], v[240:241]
	v_pk_fma_f32 v[242:243], v[168:169], v[16:17], v[242:243]
	global_load_dword v2, v0, s[22:23] nt
	s_add_u32 s22, s22, 0x6000
	s_addc_u32 s23, s23, 0
	global_load_dword v3, v0, s[22:23] nt
	s_add_u32 s22, s22, 0x6000
	s_addc_u32 s23, s23, 0
	global_load_dword v4, v0, s[22:23] nt
	s_add_u32 s22, s22, 0x6000
	s_addc_u32 s23, s23, 0
	global_load_dword v5, v0, s[22:23] nt
	s_add_u32 s22, s22, 0x6000
	s_addc_u32 s23, s23, 0
	global_load_dword v6, v0, s[22:23] nt
	s_add_u32 s22, s22, 0x6000
	s_addc_u32 s23, s23, 0
	global_load_dword v7, v0, s[22:23] nt
	s_add_u32 s22, s22, 0x6000
	s_addc_u32 s23, s23, 0
	global_load_dword v8, v0, s[22:23] nt
	s_add_u32 s22, s22, 0x6000
	s_addc_u32 s23, s23, 0
	global_load_dword v9, v0, s[22:23] nt
	s_add_u32 s22, s22, 0x6000
	s_addc_u32 s23, s23, 0
	global_load_dword v10, v0, s[22:23] nt
	s_add_u32 s22, s22, 0x6000
	s_addc_u32 s23, s23, 0
	global_load_dword v11, v0, s[22:23] nt
	s_add_u32 s22, s22, 0x6000
	s_addc_u32 s23, s23, 0
	global_load_dword v12, v0, s[22:23] nt
	s_add_u32 s22, s22, 0x6000
	s_addc_u32 s23, s23, 0
	global_load_dword v13, v0, s[22:23] nt
	s_add_u32 s22, s22, 0x6000
	s_addc_u32 s23, s23, 0
	global_load_dword v14, v0, s[22:23] nt
	s_add_u32 s22, s22, 0x6000
	s_addc_u32 s23, s23, 0
	global_load_dword v15, v0, s[22:23] nt
	s_add_u32 s22, s22, 0x6000
	s_addc_u32 s23, s23, 0
	global_load_dword v16, v0, s[22:23] nt
	s_add_u32 s22, s22, 0x6000
	s_addc_u32 s23, s23, 0
	global_load_dword v17, v0, s[22:23] nt
	s_add_u32 s22, s22, 0x6000
	s_addc_u32 s23, s23, 0
	s_waitcnt vmcnt(16)
	ds_read_b128 v[134:137], v1 offset:80
	ds_read_b128 v[138:141], v1 offset:4176
	ds_read_b128 v[142:145], v1 offset:8272
	ds_read_b128 v[146:149], v1 offset:12368
	ds_read_b128 v[150:153], v1 offset:16464
	ds_read_b128 v[154:157], v1 offset:20560
	ds_read_b128 v[158:161], v1 offset:24656
	ds_read_b128 v[162:165], v1 offset:28752
	ds_read_b128 v[166:169], v1 offset:32848
	s_waitcnt lgkmcnt(9)
; #define LAS __attribute__((address_space(3)))
; __device__ __forceinline__ void prologue(const __attribute__((address_space(4))) Args& a, ldsp lds, int gw, int NGW, int wave, int lane, const int tid, const int bid, const int G) {
;     ...
;         for (int k = wave * 128; k < wave * 128 + 128; k += 16) {
;             float wv[16];
; #pragma unroll
;             for (int q = 0; q < 16; ++q) wv[q] = Wl[(size_t)(k + q) * NMOD];
; #pragma unroll
;             for (int q4 = 0; q4 < 4; ++q4)
; #pragma unroll
;                 for (int j = 0; j < 9; ++j) { const f32x4 s4 = *(const LAS f32x4*)(sc + j * D + k + 4 * q4); acc[j] += s4[0] * wv[4 * q4] + s4[1] * wv[4 * q4 + 1] + s4[2] * wv[4 * q4 + 2] + s4[3] * wv[4 * q4 + 3]; }
	v_pk_fma_f32 v[226:227], v[98:99], v[34:35], v[226:227]
	v_pk_fma_f32 v[228:229], v[102:103], v[34:35], v[228:229]
	v_pk_fma_f32 v[230:231], v[106:107], v[34:35], v[230:231]
	v_pk_fma_f32 v[232:233], v[110:111], v[34:35], v[232:233]
	v_pk_fma_f32 v[234:235], v[114:115], v[34:35], v[234:235]
	v_pk_fma_f32 v[236:237], v[118:119], v[34:35], v[236:237]
	v_pk_fma_f32 v[238:239], v[122:123], v[34:35], v[238:239]
	v_pk_fma_f32 v[240:241], v[126:127], v[34:35], v[240:241]
	v_pk_fma_f32 v[242:243], v[130:131], v[34:35], v[242:243]
	v_pk_fma_f32 v[226:227], v[100:101], v[36:37], v[226:227]
	v_pk_fma_f32 v[228:229], v[104:105], v[36:37], v[228:229]
	v_pk_fma_f32 v[230:231], v[108:109], v[36:37], v[230:231]
	v_pk_fma_f32 v[232:233], v[112:113], v[36:37], v[232:233]
	v_pk_fma_f32 v[234:235], v[116:117], v[36:37], v[234:235]
	v_pk_fma_f32 v[236:237], v[120:121], v[36:37], v[236:237]
	v_pk_fma_f32 v[238:239], v[124:125], v[36:37], v[238:239]
	v_pk_fma_f32 v[240:241], v[128:129], v[36:37], v[240:241]
	v_pk_fma_f32 v[242:243], v[132:133], v[36:37], v[242:243]
	ds_read_b128 v[98:101], v1 offset:96
	ds_read_b128 v[102:105], v1 offset:4192
	ds_read_b128 v[106:109], v1 offset:8288
	ds_read_b128 v[110:113], v1 offset:12384
	ds_read_b128 v[114:117], v1 offset:16480
	ds_read_b128 v[118:121], v1 offset:20576
	ds_read_b128 v[122:125], v1 offset:24672
	ds_read_b128 v[126:129], v1 offset:28768
	ds_read_b128 v[130:133], v1 offset:32864
	s_waitcnt lgkmcnt(9)
	v_pk_fma_f32 v[226:227], v[134:135], v[38:39], v[226:227]
	v_pk_fma_f32 v[228:229], v[138:139], v[38:39], v[228:229]
	v_pk_fma_f32 v[230:231], v[142:143], v[38:39], v[230:231]
	v_pk_fma_f32 v[232:233], v[146:147], v[38:39], v[232:233]
	v_pk_fma_f32 v[234:235], v[150:151], v[38:39], v[234:235]
	v_pk_fma_f32 v[236:237], v[154:155], v[38:39], v[236:237]
	v_pk_fma_f32 v[238:239], v[158:159], v[38:39], v[238:239]
	v_pk_fma_f32 v[240:241], v[162:163], v[38:39], v[240:241]
	v_pk_fma_f32 v[242:243], v[166:167], v[38:39], v[242:243]
	v_pk_fma_f32 v[226:227], v[136:137], v[40:41], v[226:227]
	v_pk_fma_f32 v[228:229], v[140:141], v[40:41], v[228:229]
	v_pk_fma_f32 v[230:231], v[144:145], v[40:41], v[230:231]
	v_pk_fma_f32 v[232:233], v[148:149], v[40:41], v[232:233]
	v_pk_fma_f32 v[234:235], v[152:153], v[40:41], v[234:235]
	v_pk_fma_f32 v[236:237], v[156:157], v[40:41], v[236:237]
	v_pk_fma_f32 v[238:239], v[160:161], v[40:41], v[238:239]
	v_pk_fma_f32 v[240:241], v[164:165], v[40:41], v[240:241]
	v_pk_fma_f32 v[242:243], v[168:169], v[40:41], v[242:243]
	ds_read_b128 v[134:137], v1 offset:112
	ds_read_b128 v[138:141], v1 offset:4208
	ds_read_b128 v[142:145], v1 offset:8304
	ds_read_b128 v[146:149], v1 offset:12400
	ds_read_b128 v[150:153], v1 offset:16496
	ds_read_b128 v[154:157], v1 offset:20592
	ds_read_b128 v[158:161], v1 offset:24688
	ds_read_b128 v[162:165], v1 offset:28784
	ds_read_b128 v[166:169], v1 offset:32880
	s_waitcnt lgkmcnt(9)
	v_pk_fma_f32 v[226:227], v[98:99], v[42:43], v[226:227]
	v_pk_fma_f32 v[228:229], v[102:103], v[42:43], v[228:229]
	v_pk_fma_f32 v[230:231], v[106:107], v[42:43], v[230:231]
	v_pk_fma_f32 v[232:233], v[110:111], v[42:43], v[232:233]
	v_pk_fma_f32 v[234:235], v[114:115], v[42:43], v[234:235]
	v_pk_fma_f32 v[236:237], v[118:119], v[42:43], v[236:237]
	v_pk_fma_f32 v[238:239], v[122:123], v[42:43], v[238:239]
	v_pk_fma_f32 v[240:241], v[126:127], v[42:43], v[240:241]
	v_pk_fma_f32 v[242:243], v[130:131], v[42:43], v[242:243]
	v_pk_fma_f32 v[226:227], v[100:101], v[44:45], v[226:227]
	v_pk_fma_f32 v[228:229], v[104:105], v[44:45], v[228:229]
	v_pk_fma_f32 v[230:231], v[108:109], v[44:45], v[230:231]
	v_pk_fma_f32 v[232:233], v[112:113], v[44:45], v[232:233]
	v_pk_fma_f32 v[234:235], v[116:117], v[44:45], v[234:235]
	v_pk_fma_f32 v[236:237], v[120:121], v[44:45], v[236:237]
	v_pk_fma_f32 v[238:239], v[124:125], v[44:45], v[238:239]
	v_pk_fma_f32 v[240:241], v[128:129], v[44:45], v[240:241]
	v_pk_fma_f32 v[242:243], v[132:133], v[44:45], v[242:243]
	ds_read_b128 v[98:101], v1 offset:128
	ds_read_b128 v[102:105], v1 offset:4224
	ds_read_b128 v[106:109], v1 offset:8320
	ds_read_b128 v[110:113], v1 offset:12416
	ds_read_b128 v[114:117], v1 offset:16512
	ds_read_b128 v[118:121], v1 offset:20608
	ds_read_b128 v[122:125], v1 offset:24704
	ds_read_b128 v[126:129], v1 offset:28800
	ds_read_b128 v[130:133], v1 offset:32896
	s_waitcnt lgkmcnt(9)
; #define LAS __attribute__((address_space(3)))
; __device__ __forceinline__ void prologue(const __attribute__((address_space(4))) Args& a, ldsp lds, int gw, int NGW, int wave, int lane, const int tid, const int bid, const int G) {
;     ...
;         for (int k = wave * 128; k < wave * 128 + 128; k += 16) {
;             float wv[16];
; #pragma unroll
;             for (int q = 0; q < 16; ++q) wv[q] = Wl[(size_t)(k + q) * NMOD];
; #pragma unroll
;             for (int q4 = 0; q4 < 4; ++q4)
; #pragma unroll
;                 for (int j = 0; j < 9; ++j) { const f32x4 s4 = *(const LAS f32x4*)(sc + j * D + k + 4 * q4); acc[j] += s4[0] * wv[4 * q4] + s4[1] * wv[4 * q4 + 1] + s4[2] * wv[4 * q4 + 2] + s4[3] * wv[4 * q4 + 3]; }
	v_pk_fma_f32 v[226:227], v[134:135], v[46:47], v[226:227]
	v_pk_fma_f32 v[228:229], v[138:139], v[46:47], v[228:229]
	v_pk_fma_f32 v[230:231], v[142:143], v[46:47], v[230:231]
	v_pk_fma_f32 v[232:233], v[146:147], v[46:47], v[232:233]
	v_pk_fma_f32 v[234:235], v[150:151], v[46:47], v[234:235]
	v_pk_fma_f32 v[236:237], v[154:155], v[46:47], v[236:237]
	v_pk_fma_f32 v[238:239], v[158:159], v[46:47], v[238:239]
	v_pk_fma_f32 v[240:241], v[162:163], v[46:47], v[240:241]
	v_pk_fma_f32 v[242:243], v[166:167], v[46:47], v[242:243]
	v_pk_fma_f32 v[226:227], v[136:137], v[48:49], v[226:227]
	v_pk_fma_f32 v[228:229], v[140:141], v[48:49], v[228:229]
	v_pk_fma_f32 v[230:231], v[144:145], v[48:49], v[230:231]
	v_pk_fma_f32 v[232:233], v[148:149], v[48:49], v[232:233]
	v_pk_fma_f32 v[234:235], v[152:153], v[48:49], v[234:235]
	v_pk_fma_f32 v[236:237], v[156:157], v[48:49], v[236:237]
	v_pk_fma_f32 v[238:239], v[160:161], v[48:49], v[238:239]
	v_pk_fma_f32 v[240:241], v[164:165], v[48:49], v[240:241]
	v_pk_fma_f32 v[242:243], v[168:169], v[48:49], v[242:243]
	global_load_dword v34, v0, s[22:23] nt
	s_add_u32 s22, s22, 0x6000
	s_addc_u32 s23, s23, 0
	global_load_dword v35, v0, s[22:23] nt
	s_add_u32 s22, s22, 0x6000
	s_addc_u32 s23, s23, 0
	global_load_dword v36, v0, s[22:23] nt
	s_add_u32 s22, s22, 0x6000
	s_addc_u32 s23, s23, 0
	global_load_dword v37, v0, s[22:23] nt
	s_add_u32 s22, s22, 0x6000
	s_addc_u32 s23, s23, 0
	global_load_dword v38, v0, s[22:23] nt
	s_add_u32 s22, s22, 0x6000
	s_addc_u32 s23, s23, 0
	global_load_dword v39, v0, s[22:23] nt
	s_add_u32 s22, s22, 0x6000
	s_addc_u32 s23, s23, 0
	global_load_dword v40, v0, s[22:23] nt
	s_add_u32 s22, s22, 0x6000
	s_addc_u32 s23, s23, 0
	global_load_dword v41, v0, s[22:23] nt
	s_add_u32 s22, s22, 0x6000
	s_addc_u32 s23, s23, 0
	global_load_dword v42, v0, s[22:23] nt
	s_add_u32 s22, s22, 0x6000
	s_addc_u32 s23, s23, 0
	global_load_dword v43, v0, s[22:23] nt
	s_add_u32 s22, s22, 0x6000
	s_addc_u32 s23, s23, 0
	global_load_dword v44, v0, s[22:23] nt
	s_add_u32 s22, s22, 0x6000
	s_addc_u32 s23, s23, 0
	global_load_dword v45, v0, s[22:23] nt
	s_add_u32 s22, s22, 0x6000
	s_addc_u32 s23, s23, 0
	global_load_dword v46, v0, s[22:23] nt
	s_add_u32 s22, s22, 0x6000
	s_addc_u32 s23, s23, 0
	global_load_dword v47, v0, s[22:23] nt
	s_add_u32 s22, s22, 0x6000
	s_addc_u32 s23, s23, 0
	global_load_dword v48, v0, s[22:23] nt
	s_add_u32 s22, s22, 0x6000
	s_addc_u32 s23, s23, 0
	global_load_dword v49, v0, s[22:23] nt
	s_add_u32 s22, s22, 0x6000
	s_addc_u32 s23, s23, 0
	s_waitcnt vmcnt(16)
	ds_read_b128 v[134:137], v1 offset:144
	ds_read_b128 v[138:141], v1 offset:4240
	ds_read_b128 v[142:145], v1 offset:8336
	ds_read_b128 v[146:149], v1 offset:12432
	ds_read_b128 v[150:153], v1 offset:16528
	ds_read_b128 v[154:157], v1 offset:20624
	ds_read_b128 v[158:161], v1 offset:24720
	ds_read_b128 v[162:165], v1 offset:28816
	ds_read_b128 v[166:169], v1 offset:32912
	s_waitcnt lgkmcnt(9)
	v_pk_fma_f32 v[226:227], v[98:99], v[2:3], v[226:227]
	v_pk_fma_f32 v[228:229], v[102:103], v[2:3], v[228:229]
	v_pk_fma_f32 v[230:231], v[106:107], v[2:3], v[230:231]
	v_pk_fma_f32 v[232:233], v[110:111], v[2:3], v[232:233]
	v_pk_fma_f32 v[234:235], v[114:115], v[2:3], v[234:235]
	v_pk_fma_f32 v[236:237], v[118:119], v[2:3], v[236:237]
	v_pk_fma_f32 v[238:239], v[122:123], v[2:3], v[238:239]
	v_pk_fma_f32 v[240:241], v[126:127], v[2:3], v[240:241]
	v_pk_fma_f32 v[242:243], v[130:131], v[2:3], v[242:243]
	v_pk_fma_f32 v[226:227], v[100:101], v[4:5], v[226:227]
	v_pk_fma_f32 v[228:229], v[104:105], v[4:5], v[228:229]
	v_pk_fma_f32 v[230:231], v[108:109], v[4:5], v[230:231]
	v_pk_fma_f32 v[232:233], v[112:113], v[4:5], v[232:233]
	v_pk_fma_f32 v[234:235], v[116:117], v[4:5], v[234:235]
	v_pk_fma_f32 v[236:237], v[120:121], v[4:5], v[236:237]
	v_pk_fma_f32 v[238:239], v[124:125], v[4:5], v[238:239]
	v_pk_fma_f32 v[240:241], v[128:129], v[4:5], v[240:241]
	v_pk_fma_f32 v[242:243], v[132:133], v[4:5], v[242:243]
	ds_read_b128 v[98:101], v1 offset:160
	ds_read_b128 v[102:105], v1 offset:4256
	ds_read_b128 v[106:109], v1 offset:8352
	ds_read_b128 v[110:113], v1 offset:12448
	ds_read_b128 v[114:117], v1 offset:16544
	ds_read_b128 v[118:121], v1 offset:20640
	ds_read_b128 v[122:125], v1 offset:24736
	ds_read_b128 v[126:129], v1 offset:28832
	ds_read_b128 v[130:133], v1 offset:32928
	s_waitcnt lgkmcnt(9)
	v_pk_fma_f32 v[226:227], v[134:135], v[6:7], v[226:227]
	v_pk_fma_f32 v[228:229], v[138:139], v[6:7], v[228:229]
	v_pk_fma_f32 v[230:231], v[142:143], v[6:7], v[230:231]
	v_pk_fma_f32 v[232:233], v[146:147], v[6:7], v[232:233]
	v_pk_fma_f32 v[234:235], v[150:151], v[6:7], v[234:235]
	v_pk_fma_f32 v[236:237], v[154:155], v[6:7], v[236:237]
	v_pk_fma_f32 v[238:239], v[158:159], v[6:7], v[238:239]
	v_pk_fma_f32 v[240:241], v[162:163], v[6:7], v[240:241]
	v_pk_fma_f32 v[242:243], v[166:167], v[6:7], v[242:243]
	v_pk_fma_f32 v[226:227], v[136:137], v[8:9], v[226:227]
	v_pk_fma_f32 v[228:229], v[140:141], v[8:9], v[228:229]
	v_pk_fma_f32 v[230:231], v[144:145], v[8:9], v[230:231]
	v_pk_fma_f32 v[232:233], v[148:149], v[8:9], v[232:233]
	v_pk_fma_f32 v[234:235], v[152:153], v[8:9], v[234:235]
	v_pk_fma_f32 v[236:237], v[156:157], v[8:9], v[236:237]
	v_pk_fma_f32 v[238:239], v[160:161], v[8:9], v[238:239]
	v_pk_fma_f32 v[240:241], v[164:165], v[8:9], v[240:241]
	v_pk_fma_f32 v[242:243], v[168:169], v[8:9], v[242:243]
	ds_read_b128 v[134:137], v1 offset:176
	ds_read_b128 v[138:141], v1 offset:4272
	ds_read_b128 v[142:145], v1 offset:8368
	ds_read_b128 v[146:149], v1 offset:12464
	ds_read_b128 v[150:153], v1 offset:16560
	ds_read_b128 v[154:157], v1 offset:20656
	ds_read_b128 v[158:161], v1 offset:24752
	ds_read_b128 v[162:165], v1 offset:28848
	ds_read_b128 v[166:169], v1 offset:32944
	s_waitcnt lgkmcnt(9)
; #define LAS __attribute__((address_space(3)))
; __device__ __forceinline__ void prologue(const __attribute__((address_space(4))) Args& a, ldsp lds, int gw, int NGW, int wave, int lane, const int tid, const int bid, const int G) {
;     ...
;         for (int k = wave * 128; k < wave * 128 + 128; k += 16) {
;             float wv[16];
; #pragma unroll
;             for (int q = 0; q < 16; ++q) wv[q] = Wl[(size_t)(k + q) * NMOD];
; #pragma unroll
;             for (int q4 = 0; q4 < 4; ++q4)
; #pragma unroll
;                 for (int j = 0; j < 9; ++j) { const f32x4 s4 = *(const LAS f32x4*)(sc + j * D + k + 4 * q4); acc[j] += s4[0] * wv[4 * q4] + s4[1] * wv[4 * q4 + 1] + s4[2] * wv[4 * q4 + 2] + s4[3] * wv[4 * q4 + 3]; }
	v_pk_fma_f32 v[226:227], v[98:99], v[10:11], v[226:227]
	v_pk_fma_f32 v[228:229], v[102:103], v[10:11], v[228:229]
	v_pk_fma_f32 v[230:231], v[106:107], v[10:11], v[230:231]
	v_pk_fma_f32 v[232:233], v[110:111], v[10:11], v[232:233]
	v_pk_fma_f32 v[234:235], v[114:115], v[10:11], v[234:235]
	v_pk_fma_f32 v[236:237], v[118:119], v[10:11], v[236:237]
	v_pk_fma_f32 v[238:239], v[122:123], v[10:11], v[238:239]
	v_pk_fma_f32 v[240:241], v[126:127], v[10:11], v[240:241]
	v_pk_fma_f32 v[242:243], v[130:131], v[10:11], v[242:243]
	v_pk_fma_f32 v[226:227], v[100:101], v[12:13], v[226:227]
	v_pk_fma_f32 v[228:229], v[104:105], v[12:13], v[228:229]
	v_pk_fma_f32 v[230:231], v[108:109], v[12:13], v[230:231]
	v_pk_fma_f32 v[232:233], v[112:113], v[12:13], v[232:233]
	v_pk_fma_f32 v[234:235], v[116:117], v[12:13], v[234:235]
	v_pk_fma_f32 v[236:237], v[120:121], v[12:13], v[236:237]
	v_pk_fma_f32 v[238:239], v[124:125], v[12:13], v[238:239]
	v_pk_fma_f32 v[240:241], v[128:129], v[12:13], v[240:241]
	v_pk_fma_f32 v[242:243], v[132:133], v[12:13], v[242:243]
	ds_read_b128 v[98:101], v1 offset:192
	ds_read_b128 v[102:105], v1 offset:4288
	ds_read_b128 v[106:109], v1 offset:8384
	ds_read_b128 v[110:113], v1 offset:12480
	ds_read_b128 v[114:117], v1 offset:16576
	ds_read_b128 v[118:121], v1 offset:20672
	ds_read_b128 v[122:125], v1 offset:24768
	ds_read_b128 v[126:129], v1 offset:28864
	ds_read_b128 v[130:133], v1 offset:32960
	s_waitcnt lgkmcnt(9)
	v_pk_fma_f32 v[226:227], v[134:135], v[14:15], v[226:227]
	v_pk_fma_f32 v[228:229], v[138:139], v[14:15], v[228:229]
	v_pk_fma_f32 v[230:231], v[142:143], v[14:15], v[230:231]
	v_pk_fma_f32 v[232:233], v[146:147], v[14:15], v[232:233]
	v_pk_fma_f32 v[234:235], v[150:151], v[14:15], v[234:235]
	v_pk_fma_f32 v[236:237], v[154:155], v[14:15], v[236:237]
	v_pk_fma_f32 v[238:239], v[158:159], v[14:15], v[238:239]
	v_pk_fma_f32 v[240:241], v[162:163], v[14:15], v[240:241]
	v_pk_fma_f32 v[242:243], v[166:167], v[14:15], v[242:243]
	v_pk_fma_f32 v[226:227], v[136:137], v[16:17], v[226:227]
	v_pk_fma_f32 v[228:229], v[140:141], v[16:17], v[228:229]
	v_pk_fma_f32 v[230:231], v[144:145], v[16:17], v[230:231]
	v_pk_fma_f32 v[232:233], v[148:149], v[16:17], v[232:233]
	v_pk_fma_f32 v[234:235], v[152:153], v[16:17], v[234:235]
	v_pk_fma_f32 v[236:237], v[156:157], v[16:17], v[236:237]
	v_pk_fma_f32 v[238:239], v[160:161], v[16:17], v[238:239]
	v_pk_fma_f32 v[240:241], v[164:165], v[16:17], v[240:241]
	v_pk_fma_f32 v[242:243], v[168:169], v[16:17], v[242:243]
	global_load_dword v2, v0, s[22:23] nt
	s_add_u32 s22, s22, 0x6000
	s_addc_u32 s23, s23, 0
	global_load_dword v3, v0, s[22:23] nt
	s_add_u32 s22, s22, 0x6000
	s_addc_u32 s23, s23, 0
	global_load_dword v4, v0, s[22:23] nt
	s_add_u32 s22, s22, 0x6000
	s_addc_u32 s23, s23, 0
	global_load_dword v5, v0, s[22:23] nt
	s_add_u32 s22, s22, 0x6000
	s_addc_u32 s23, s23, 0
	global_load_dword v6, v0, s[22:23] nt
	s_add_u32 s22, s22, 0x6000
	s_addc_u32 s23, s23, 0
	global_load_dword v7, v0, s[22:23] nt
	s_add_u32 s22, s22, 0x6000
	s_addc_u32 s23, s23, 0
	global_load_dword v8, v0, s[22:23] nt
	s_add_u32 s22, s22, 0x6000
	s_addc_u32 s23, s23, 0
	global_load_dword v9, v0, s[22:23] nt
	s_add_u32 s22, s22, 0x6000
	s_addc_u32 s23, s23, 0
	global_load_dword v10, v0, s[22:23] nt
	s_add_u32 s22, s22, 0x6000
	s_addc_u32 s23, s23, 0
	global_load_dword v11, v0, s[22:23] nt
	s_add_u32 s22, s22, 0x6000
	s_addc_u32 s23, s23, 0
	global_load_dword v12, v0, s[22:23] nt
	s_add_u32 s22, s22, 0x6000
	s_addc_u32 s23, s23, 0
	global_load_dword v13, v0, s[22:23] nt
	s_add_u32 s22, s22, 0x6000
	s_addc_u32 s23, s23, 0
	global_load_dword v14, v0, s[22:23] nt
	s_add_u32 s22, s22, 0x6000
	s_addc_u32 s23, s23, 0
	global_load_dword v15, v0, s[22:23] nt
	s_add_u32 s22, s22, 0x6000
	s_addc_u32 s23, s23, 0
	global_load_dword v16, v0, s[22:23] nt
	s_add_u32 s22, s22, 0x6000
	s_addc_u32 s23, s23, 0
	global_load_dword v17, v0, s[22:23] nt
	s_add_u32 s22, s22, 0x6000
	s_addc_u32 s23, s23, 0
	s_waitcnt vmcnt(16)
	ds_read_b128 v[134:137], v1 offset:208
	ds_read_b128 v[138:141], v1 offset:4304
	ds_read_b128 v[142:145], v1 offset:8400
	ds_read_b128 v[146:149], v1 offset:12496
	ds_read_b128 v[150:153], v1 offset:16592
	ds_read_b128 v[154:157], v1 offset:20688
	ds_read_b128 v[158:161], v1 offset:24784
	ds_read_b128 v[162:165], v1 offset:28880
	ds_read_b128 v[166:169], v1 offset:32976
	s_waitcnt lgkmcnt(9)
	v_pk_fma_f32 v[226:227], v[98:99], v[34:35], v[226:227]
	v_pk_fma_f32 v[228:229], v[102:103], v[34:35], v[228:229]
	v_pk_fma_f32 v[230:231], v[106:107], v[34:35], v[230:231]
	v_pk_fma_f32 v[232:233], v[110:111], v[34:35], v[232:233]
	v_pk_fma_f32 v[234:235], v[114:115], v[34:35], v[234:235]
	v_pk_fma_f32 v[236:237], v[118:119], v[34:35], v[236:237]
	v_pk_fma_f32 v[238:239], v[122:123], v[34:35], v[238:239]
	v_pk_fma_f32 v[240:241], v[126:127], v[34:35], v[240:241]
	v_pk_fma_f32 v[242:243], v[130:131], v[34:35], v[242:243]
	v_pk_fma_f32 v[226:227], v[100:101], v[36:37], v[226:227]
	v_pk_fma_f32 v[228:229], v[104:105], v[36:37], v[228:229]
	v_pk_fma_f32 v[230:231], v[108:109], v[36:37], v[230:231]
	v_pk_fma_f32 v[232:233], v[112:113], v[36:37], v[232:233]
	v_pk_fma_f32 v[234:235], v[116:117], v[36:37], v[234:235]
	v_pk_fma_f32 v[236:237], v[120:121], v[36:37], v[236:237]
	v_pk_fma_f32 v[238:239], v[124:125], v[36:37], v[238:239]
	v_pk_fma_f32 v[240:241], v[128:129], v[36:37], v[240:241]
	v_pk_fma_f32 v[242:243], v[132:133], v[36:37], v[242:243]
	ds_read_b128 v[98:101], v1 offset:224
	ds_read_b128 v[102:105], v1 offset:4320
	ds_read_b128 v[106:109], v1 offset:8416
	ds_read_b128 v[110:113], v1 offset:12512
	ds_read_b128 v[114:117], v1 offset:16608
	ds_read_b128 v[118:121], v1 offset:20704
	ds_read_b128 v[122:125], v1 offset:24800
	ds_read_b128 v[126:129], v1 offset:28896
	ds_read_b128 v[130:133], v1 offset:32992
	s_waitcnt lgkmcnt(9)
; #define LAS __attribute__((address_space(3)))
; __device__ __forceinline__ void prologue(const __attribute__((address_space(4))) Args& a, ldsp lds, int gw, int NGW, int wave, int lane, const int tid, const int bid, const int G) {
;     ...
;         for (int k = wave * 128; k < wave * 128 + 128; k += 16) {
;             float wv[16];
; #pragma unroll
;             for (int q = 0; q < 16; ++q) wv[q] = Wl[(size_t)(k + q) * NMOD];
; #pragma unroll
;             for (int q4 = 0; q4 < 4; ++q4)
; #pragma unroll
;                 for (int j = 0; j < 9; ++j) { const f32x4 s4 = *(const LAS f32x4*)(sc + j * D + k + 4 * q4); acc[j] += s4[0] * wv[4 * q4] + s4[1] * wv[4 * q4 + 1] + s4[2] * wv[4 * q4 + 2] + s4[3] * wv[4 * q4 + 3]; }
	v_pk_fma_f32 v[226:227], v[134:135], v[38:39], v[226:227]
	v_pk_fma_f32 v[228:229], v[138:139], v[38:39], v[228:229]
	v_pk_fma_f32 v[230:231], v[142:143], v[38:39], v[230:231]
	v_pk_fma_f32 v[232:233], v[146:147], v[38:39], v[232:233]
	v_pk_fma_f32 v[234:235], v[150:151], v[38:39], v[234:235]
	v_pk_fma_f32 v[236:237], v[154:155], v[38:39], v[236:237]
	v_pk_fma_f32 v[238:239], v[158:159], v[38:39], v[238:239]
	v_pk_fma_f32 v[240:241], v[162:163], v[38:39], v[240:241]
	v_pk_fma_f32 v[242:243], v[166:167], v[38:39], v[242:243]
	v_pk_fma_f32 v[226:227], v[136:137], v[40:41], v[226:227]
	v_pk_fma_f32 v[228:229], v[140:141], v[40:41], v[228:229]
	v_pk_fma_f32 v[230:231], v[144:145], v[40:41], v[230:231]
	v_pk_fma_f32 v[232:233], v[148:149], v[40:41], v[232:233]
	v_pk_fma_f32 v[234:235], v[152:153], v[40:41], v[234:235]
	v_pk_fma_f32 v[236:237], v[156:157], v[40:41], v[236:237]
	v_pk_fma_f32 v[238:239], v[160:161], v[40:41], v[238:239]
	v_pk_fma_f32 v[240:241], v[164:165], v[40:41], v[240:241]
	v_pk_fma_f32 v[242:243], v[168:169], v[40:41], v[242:243]
	ds_read_b128 v[134:137], v1 offset:240
	ds_read_b128 v[138:141], v1 offset:4336
	ds_read_b128 v[142:145], v1 offset:8432
	ds_read_b128 v[146:149], v1 offset:12528
	ds_read_b128 v[150:153], v1 offset:16624
	ds_read_b128 v[154:157], v1 offset:20720
	ds_read_b128 v[158:161], v1 offset:24816
	ds_read_b128 v[162:165], v1 offset:28912
	ds_read_b128 v[166:169], v1 offset:33008
	s_waitcnt lgkmcnt(9)
	v_pk_fma_f32 v[226:227], v[98:99], v[42:43], v[226:227]
	v_pk_fma_f32 v[228:229], v[102:103], v[42:43], v[228:229]
	v_pk_fma_f32 v[230:231], v[106:107], v[42:43], v[230:231]
	v_pk_fma_f32 v[232:233], v[110:111], v[42:43], v[232:233]
	v_pk_fma_f32 v[234:235], v[114:115], v[42:43], v[234:235]
	v_pk_fma_f32 v[236:237], v[118:119], v[42:43], v[236:237]
	v_pk_fma_f32 v[238:239], v[122:123], v[42:43], v[238:239]
	v_pk_fma_f32 v[240:241], v[126:127], v[42:43], v[240:241]
	v_pk_fma_f32 v[242:243], v[130:131], v[42:43], v[242:243]
	v_pk_fma_f32 v[226:227], v[100:101], v[44:45], v[226:227]
	v_pk_fma_f32 v[228:229], v[104:105], v[44:45], v[228:229]
	v_pk_fma_f32 v[230:231], v[108:109], v[44:45], v[230:231]
	v_pk_fma_f32 v[232:233], v[112:113], v[44:45], v[232:233]
	v_pk_fma_f32 v[234:235], v[116:117], v[44:45], v[234:235]
	v_pk_fma_f32 v[236:237], v[120:121], v[44:45], v[236:237]
	v_pk_fma_f32 v[238:239], v[124:125], v[44:45], v[238:239]
	v_pk_fma_f32 v[240:241], v[128:129], v[44:45], v[240:241]
	v_pk_fma_f32 v[242:243], v[132:133], v[44:45], v[242:243]
	ds_read_b128 v[98:101], v1 offset:256
	ds_read_b128 v[102:105], v1 offset:4352
	ds_read_b128 v[106:109], v1 offset:8448
	ds_read_b128 v[110:113], v1 offset:12544
	ds_read_b128 v[114:117], v1 offset:16640
	ds_read_b128 v[118:121], v1 offset:20736
	ds_read_b128 v[122:125], v1 offset:24832
	ds_read_b128 v[126:129], v1 offset:28928
	ds_read_b128 v[130:133], v1 offset:33024
	s_waitcnt lgkmcnt(9)
	v_pk_fma_f32 v[226:227], v[134:135], v[46:47], v[226:227]
	v_pk_fma_f32 v[228:229], v[138:139], v[46:47], v[228:229]
	v_pk_fma_f32 v[230:231], v[142:143], v[46:47], v[230:231]
	v_pk_fma_f32 v[232:233], v[146:147], v[46:47], v[232:233]
	v_pk_fma_f32 v[234:235], v[150:151], v[46:47], v[234:235]
	v_pk_fma_f32 v[236:237], v[154:155], v[46:47], v[236:237]
	v_pk_fma_f32 v[238:239], v[158:159], v[46:47], v[238:239]
	v_pk_fma_f32 v[240:241], v[162:163], v[46:47], v[240:241]
	v_pk_fma_f32 v[242:243], v[166:167], v[46:47], v[242:243]
	v_pk_fma_f32 v[226:227], v[136:137], v[48:49], v[226:227]
	v_pk_fma_f32 v[228:229], v[140:141], v[48:49], v[228:229]
	v_pk_fma_f32 v[230:231], v[144:145], v[48:49], v[230:231]
	v_pk_fma_f32 v[232:233], v[148:149], v[48:49], v[232:233]
	v_pk_fma_f32 v[234:235], v[152:153], v[48:49], v[234:235]
	v_pk_fma_f32 v[236:237], v[156:157], v[48:49], v[236:237]
	v_pk_fma_f32 v[238:239], v[160:161], v[48:49], v[238:239]
	v_pk_fma_f32 v[240:241], v[164:165], v[48:49], v[240:241]
	v_pk_fma_f32 v[242:243], v[168:169], v[48:49], v[242:243]
	global_load_dword v34, v0, s[22:23] nt
	s_add_u32 s22, s22, 0x6000
	s_addc_u32 s23, s23, 0
	global_load_dword v35, v0, s[22:23] nt
	s_add_u32 s22, s22, 0x6000
	s_addc_u32 s23, s23, 0
	global_load_dword v36, v0, s[22:23] nt
	s_add_u32 s22, s22, 0x6000
	s_addc_u32 s23, s23, 0
	global_load_dword v37, v0, s[22:23] nt
	s_add_u32 s22, s22, 0x6000
	s_addc_u32 s23, s23, 0
	global_load_dword v38, v0, s[22:23] nt
	s_add_u32 s22, s22, 0x6000
	s_addc_u32 s23, s23, 0
	global_load_dword v39, v0, s[22:23] nt
	s_add_u32 s22, s22, 0x6000
	s_addc_u32 s23, s23, 0
	global_load_dword v40, v0, s[22:23] nt
	s_add_u32 s22, s22, 0x6000
	s_addc_u32 s23, s23, 0
	global_load_dword v41, v0, s[22:23] nt
	s_add_u32 s22, s22, 0x6000
	s_addc_u32 s23, s23, 0
	global_load_dword v42, v0, s[22:23] nt
	s_add_u32 s22, s22, 0x6000
	s_addc_u32 s23, s23, 0
	global_load_dword v43, v0, s[22:23] nt
	s_add_u32 s22, s22, 0x6000
	s_addc_u32 s23, s23, 0
	global_load_dword v44, v0, s[22:23] nt
	s_add_u32 s22, s22, 0x6000
	s_addc_u32 s23, s23, 0
	global_load_dword v45, v0, s[22:23] nt
	s_add_u32 s22, s22, 0x6000
	s_addc_u32 s23, s23, 0
	global_load_dword v46, v0, s[22:23] nt
	s_add_u32 s22, s22, 0x6000
	s_addc_u32 s23, s23, 0
	global_load_dword v47, v0, s[22:23] nt
	s_add_u32 s22, s22, 0x6000
	s_addc_u32 s23, s23, 0
	global_load_dword v48, v0, s[22:23] nt
	s_add_u32 s22, s22, 0x6000
	s_addc_u32 s23, s23, 0
	global_load_dword v49, v0, s[22:23] nt
	s_add_u32 s22, s22, 0x6000
	s_addc_u32 s23, s23, 0
	s_waitcnt vmcnt(16)
; #define LAS __attribute__((address_space(3)))
; __device__ __forceinline__ void prologue(const __attribute__((address_space(4))) Args& a, ldsp lds, int gw, int NGW, int wave, int lane, const int tid, const int bid, const int G) {
;     ...
; #pragma unroll
;             for (int q4 = 0; q4 < 4; ++q4)
; #pragma unroll
;                 for (int j = 0; j < 9; ++j) { const f32x4 s4 = *(const LAS f32x4*)(sc + j * D + k + 4 * q4); acc[j] += s4[0] * wv[4 * q4] + s4[1] * wv[4 * q4 + 1] + s4[2] * wv[4 * q4 + 2] + s4[3] * wv[4 * q4 + 3]; }
	ds_read_b128 v[134:137], v1 offset:272
	ds_read_b128 v[138:141], v1 offset:4368
	ds_read_b128 v[142:145], v1 offset:8464
	ds_read_b128 v[146:149], v1 offset:12560
	ds_read_b128 v[150:153], v1 offset:16656
	ds_read_b128 v[154:157], v1 offset:20752
	ds_read_b128 v[158:161], v1 offset:24848
	ds_read_b128 v[162:165], v1 offset:28944
	ds_read_b128 v[166:169], v1 offset:33040
	s_waitcnt lgkmcnt(9)
	v_pk_fma_f32 v[226:227], v[98:99], v[2:3], v[226:227]
	v_pk_fma_f32 v[228:229], v[102:103], v[2:3], v[228:229]
	v_pk_fma_f32 v[230:231], v[106:107], v[2:3], v[230:231]
	v_pk_fma_f32 v[232:233], v[110:111], v[2:3], v[232:233]
	v_pk_fma_f32 v[234:235], v[114:115], v[2:3], v[234:235]
	v_pk_fma_f32 v[236:237], v[118:119], v[2:3], v[236:237]
	v_pk_fma_f32 v[238:239], v[122:123], v[2:3], v[238:239]
	v_pk_fma_f32 v[240:241], v[126:127], v[2:3], v[240:241]
	v_pk_fma_f32 v[242:243], v[130:131], v[2:3], v[242:243]
	v_pk_fma_f32 v[226:227], v[100:101], v[4:5], v[226:227]
	v_pk_fma_f32 v[228:229], v[104:105], v[4:5], v[228:229]
	v_pk_fma_f32 v[230:231], v[108:109], v[4:5], v[230:231]
	v_pk_fma_f32 v[232:233], v[112:113], v[4:5], v[232:233]
	v_pk_fma_f32 v[234:235], v[116:117], v[4:5], v[234:235]
	v_pk_fma_f32 v[236:237], v[120:121], v[4:5], v[236:237]
	v_pk_fma_f32 v[238:239], v[124:125], v[4:5], v[238:239]
	v_pk_fma_f32 v[240:241], v[128:129], v[4:5], v[240:241]
	v_pk_fma_f32 v[242:243], v[132:133], v[4:5], v[242:243]
	ds_read_b128 v[98:101], v1 offset:288
	ds_read_b128 v[102:105], v1 offset:4384
	ds_read_b128 v[106:109], v1 offset:8480
	ds_read_b128 v[110:113], v1 offset:12576
	ds_read_b128 v[114:117], v1 offset:16672
	ds_read_b128 v[118:121], v1 offset:20768
	ds_read_b128 v[122:125], v1 offset:24864
	ds_read_b128 v[126:129], v1 offset:28960
	ds_read_b128 v[130:133], v1 offset:33056
	s_waitcnt lgkmcnt(9)
	v_pk_fma_f32 v[226:227], v[134:135], v[6:7], v[226:227]
	v_pk_fma_f32 v[228:229], v[138:139], v[6:7], v[228:229]
	v_pk_fma_f32 v[230:231], v[142:143], v[6:7], v[230:231]
	v_pk_fma_f32 v[232:233], v[146:147], v[6:7], v[232:233]
	v_pk_fma_f32 v[234:235], v[150:151], v[6:7], v[234:235]
	v_pk_fma_f32 v[236:237], v[154:155], v[6:7], v[236:237]
	v_pk_fma_f32 v[238:239], v[158:159], v[6:7], v[238:239]
	v_pk_fma_f32 v[240:241], v[162:163], v[6:7], v[240:241]
	v_pk_fma_f32 v[242:243], v[166:167], v[6:7], v[242:243]
	v_pk_fma_f32 v[226:227], v[136:137], v[8:9], v[226:227]
	v_pk_fma_f32 v[228:229], v[140:141], v[8:9], v[228:229]
	v_pk_fma_f32 v[230:231], v[144:145], v[8:9], v[230:231]
	v_pk_fma_f32 v[232:233], v[148:149], v[8:9], v[232:233]
	v_pk_fma_f32 v[234:235], v[152:153], v[8:9], v[234:235]
	v_pk_fma_f32 v[236:237], v[156:157], v[8:9], v[236:237]
	v_pk_fma_f32 v[238:239], v[160:161], v[8:9], v[238:239]
	v_pk_fma_f32 v[240:241], v[164:165], v[8:9], v[240:241]
	v_pk_fma_f32 v[242:243], v[168:169], v[8:9], v[242:243]
	ds_read_b128 v[134:137], v1 offset:304
	ds_read_b128 v[138:141], v1 offset:4400
	ds_read_b128 v[142:145], v1 offset:8496
	ds_read_b128 v[146:149], v1 offset:12592
	ds_read_b128 v[150:153], v1 offset:16688
	ds_read_b128 v[154:157], v1 offset:20784
	ds_read_b128 v[158:161], v1 offset:24880
	ds_read_b128 v[162:165], v1 offset:28976
	ds_read_b128 v[166:169], v1 offset:33072
	s_waitcnt lgkmcnt(9)
	v_pk_fma_f32 v[226:227], v[98:99], v[10:11], v[226:227]
	v_pk_fma_f32 v[228:229], v[102:103], v[10:11], v[228:229]
	v_pk_fma_f32 v[230:231], v[106:107], v[10:11], v[230:231]
	v_pk_fma_f32 v[232:233], v[110:111], v[10:11], v[232:233]
	v_pk_fma_f32 v[234:235], v[114:115], v[10:11], v[234:235]
	v_pk_fma_f32 v[236:237], v[118:119], v[10:11], v[236:237]
	v_pk_fma_f32 v[238:239], v[122:123], v[10:11], v[238:239]
	v_pk_fma_f32 v[240:241], v[126:127], v[10:11], v[240:241]
	v_pk_fma_f32 v[242:243], v[130:131], v[10:11], v[242:243]
	v_pk_fma_f32 v[226:227], v[100:101], v[12:13], v[226:227]
	v_pk_fma_f32 v[228:229], v[104:105], v[12:13], v[228:229]
	v_pk_fma_f32 v[230:231], v[108:109], v[12:13], v[230:231]
	v_pk_fma_f32 v[232:233], v[112:113], v[12:13], v[232:233]
	v_pk_fma_f32 v[234:235], v[116:117], v[12:13], v[234:235]
	v_pk_fma_f32 v[236:237], v[120:121], v[12:13], v[236:237]
	v_pk_fma_f32 v[238:239], v[124:125], v[12:13], v[238:239]
	v_pk_fma_f32 v[240:241], v[128:129], v[12:13], v[240:241]
	v_pk_fma_f32 v[242:243], v[132:133], v[12:13], v[242:243]
	ds_read_b128 v[98:101], v1 offset:320
	ds_read_b128 v[102:105], v1 offset:4416
	ds_read_b128 v[106:109], v1 offset:8512
	ds_read_b128 v[110:113], v1 offset:12608
	ds_read_b128 v[114:117], v1 offset:16704
	ds_read_b128 v[118:121], v1 offset:20800
	ds_read_b128 v[122:125], v1 offset:24896
	ds_read_b128 v[126:129], v1 offset:28992
	ds_read_b128 v[130:133], v1 offset:33088
	s_waitcnt lgkmcnt(9)
; #define LAS __attribute__((address_space(3)))
; __device__ __forceinline__ void prologue(const __attribute__((address_space(4))) Args& a, ldsp lds, int gw, int NGW, int wave, int lane, const int tid, const int bid, const int G) {
;     ...
;         for (int k = wave * 128; k < wave * 128 + 128; k += 16) {
;             float wv[16];
; #pragma unroll
;             for (int q = 0; q < 16; ++q) wv[q] = Wl[(size_t)(k + q) * NMOD];
; #pragma unroll
;             for (int q4 = 0; q4 < 4; ++q4)
; #pragma unroll
;                 for (int j = 0; j < 9; ++j) { const f32x4 s4 = *(const LAS f32x4*)(sc + j * D + k + 4 * q4); acc[j] += s4[0] * wv[4 * q4] + s4[1] * wv[4 * q4 + 1] + s4[2] * wv[4 * q4 + 2] + s4[3] * wv[4 * q4 + 3]; }
	v_pk_fma_f32 v[226:227], v[134:135], v[14:15], v[226:227]
	v_pk_fma_f32 v[228:229], v[138:139], v[14:15], v[228:229]
	v_pk_fma_f32 v[230:231], v[142:143], v[14:15], v[230:231]
	v_pk_fma_f32 v[232:233], v[146:147], v[14:15], v[232:233]
	v_pk_fma_f32 v[234:235], v[150:151], v[14:15], v[234:235]
	v_pk_fma_f32 v[236:237], v[154:155], v[14:15], v[236:237]
	v_pk_fma_f32 v[238:239], v[158:159], v[14:15], v[238:239]
	v_pk_fma_f32 v[240:241], v[162:163], v[14:15], v[240:241]
	v_pk_fma_f32 v[242:243], v[166:167], v[14:15], v[242:243]
	v_pk_fma_f32 v[226:227], v[136:137], v[16:17], v[226:227]
	v_pk_fma_f32 v[228:229], v[140:141], v[16:17], v[228:229]
	v_pk_fma_f32 v[230:231], v[144:145], v[16:17], v[230:231]
	v_pk_fma_f32 v[232:233], v[148:149], v[16:17], v[232:233]
	v_pk_fma_f32 v[234:235], v[152:153], v[16:17], v[234:235]
	v_pk_fma_f32 v[236:237], v[156:157], v[16:17], v[236:237]
	v_pk_fma_f32 v[238:239], v[160:161], v[16:17], v[238:239]
	v_pk_fma_f32 v[240:241], v[164:165], v[16:17], v[240:241]
	v_pk_fma_f32 v[242:243], v[168:169], v[16:17], v[242:243]
	global_load_dword v2, v0, s[22:23] nt
	s_add_u32 s22, s22, 0x6000
	s_addc_u32 s23, s23, 0
	global_load_dword v3, v0, s[22:23] nt
	s_add_u32 s22, s22, 0x6000
	s_addc_u32 s23, s23, 0
	global_load_dword v4, v0, s[22:23] nt
	s_add_u32 s22, s22, 0x6000
	s_addc_u32 s23, s23, 0
	global_load_dword v5, v0, s[22:23] nt
	s_add_u32 s22, s22, 0x6000
	s_addc_u32 s23, s23, 0
	global_load_dword v6, v0, s[22:23] nt
	s_add_u32 s22, s22, 0x6000
	s_addc_u32 s23, s23, 0
	global_load_dword v7, v0, s[22:23] nt
	s_add_u32 s22, s22, 0x6000
	s_addc_u32 s23, s23, 0
	global_load_dword v8, v0, s[22:23] nt
	s_add_u32 s22, s22, 0x6000
	s_addc_u32 s23, s23, 0
	global_load_dword v9, v0, s[22:23] nt
	s_add_u32 s22, s22, 0x6000
	s_addc_u32 s23, s23, 0
	global_load_dword v10, v0, s[22:23] nt
	s_add_u32 s22, s22, 0x6000
	s_addc_u32 s23, s23, 0
	global_load_dword v11, v0, s[22:23] nt
	s_add_u32 s22, s22, 0x6000
	s_addc_u32 s23, s23, 0
	global_load_dword v12, v0, s[22:23] nt
	s_add_u32 s22, s22, 0x6000
	s_addc_u32 s23, s23, 0
	global_load_dword v13, v0, s[22:23] nt
	s_add_u32 s22, s22, 0x6000
	s_addc_u32 s23, s23, 0
	global_load_dword v14, v0, s[22:23] nt
	s_add_u32 s22, s22, 0x6000
	s_addc_u32 s23, s23, 0
	global_load_dword v15, v0, s[22:23] nt
	s_add_u32 s22, s22, 0x6000
	s_addc_u32 s23, s23, 0
	global_load_dword v16, v0, s[22:23] nt
	s_add_u32 s22, s22, 0x6000
	s_addc_u32 s23, s23, 0
	global_load_dword v17, v0, s[22:23] nt
	s_add_u32 s22, s22, 0x6000
	s_addc_u32 s23, s23, 0
	s_waitcnt vmcnt(16)
	ds_read_b128 v[134:137], v1 offset:336
	ds_read_b128 v[138:141], v1 offset:4432
	ds_read_b128 v[142:145], v1 offset:8528
	ds_read_b128 v[146:149], v1 offset:12624
	ds_read_b128 v[150:153], v1 offset:16720
	ds_read_b128 v[154:157], v1 offset:20816
	ds_read_b128 v[158:161], v1 offset:24912
	ds_read_b128 v[162:165], v1 offset:29008
	ds_read_b128 v[166:169], v1 offset:33104
	s_waitcnt lgkmcnt(9)
	v_pk_fma_f32 v[226:227], v[98:99], v[34:35], v[226:227]
	v_pk_fma_f32 v[228:229], v[102:103], v[34:35], v[228:229]
	v_pk_fma_f32 v[230:231], v[106:107], v[34:35], v[230:231]
	v_pk_fma_f32 v[232:233], v[110:111], v[34:35], v[232:233]
	v_pk_fma_f32 v[234:235], v[114:115], v[34:35], v[234:235]
	v_pk_fma_f32 v[236:237], v[118:119], v[34:35], v[236:237]
	v_pk_fma_f32 v[238:239], v[122:123], v[34:35], v[238:239]
	v_pk_fma_f32 v[240:241], v[126:127], v[34:35], v[240:241]
	v_pk_fma_f32 v[242:243], v[130:131], v[34:35], v[242:243]
	v_pk_fma_f32 v[226:227], v[100:101], v[36:37], v[226:227]
	v_pk_fma_f32 v[228:229], v[104:105], v[36:37], v[228:229]
	v_pk_fma_f32 v[230:231], v[108:109], v[36:37], v[230:231]
	v_pk_fma_f32 v[232:233], v[112:113], v[36:37], v[232:233]
	v_pk_fma_f32 v[234:235], v[116:117], v[36:37], v[234:235]
	v_pk_fma_f32 v[236:237], v[120:121], v[36:37], v[236:237]
	v_pk_fma_f32 v[238:239], v[124:125], v[36:37], v[238:239]
	v_pk_fma_f32 v[240:241], v[128:129], v[36:37], v[240:241]
	v_pk_fma_f32 v[242:243], v[132:133], v[36:37], v[242:243]
	ds_read_b128 v[98:101], v1 offset:352
	ds_read_b128 v[102:105], v1 offset:4448
	ds_read_b128 v[106:109], v1 offset:8544
	ds_read_b128 v[110:113], v1 offset:12640
	ds_read_b128 v[114:117], v1 offset:16736
	ds_read_b128 v[118:121], v1 offset:20832
	ds_read_b128 v[122:125], v1 offset:24928
	ds_read_b128 v[126:129], v1 offset:29024
	ds_read_b128 v[130:133], v1 offset:33120
	s_waitcnt lgkmcnt(9)
	v_pk_fma_f32 v[226:227], v[134:135], v[38:39], v[226:227]
	v_pk_fma_f32 v[228:229], v[138:139], v[38:39], v[228:229]
	v_pk_fma_f32 v[230:231], v[142:143], v[38:39], v[230:231]
	v_pk_fma_f32 v[232:233], v[146:147], v[38:39], v[232:233]
	v_pk_fma_f32 v[234:235], v[150:151], v[38:39], v[234:235]
	v_pk_fma_f32 v[236:237], v[154:155], v[38:39], v[236:237]
	v_pk_fma_f32 v[238:239], v[158:159], v[38:39], v[238:239]
	v_pk_fma_f32 v[240:241], v[162:163], v[38:39], v[240:241]
	v_pk_fma_f32 v[242:243], v[166:167], v[38:39], v[242:243]
	v_pk_fma_f32 v[226:227], v[136:137], v[40:41], v[226:227]
	v_pk_fma_f32 v[228:229], v[140:141], v[40:41], v[228:229]
	v_pk_fma_f32 v[230:231], v[144:145], v[40:41], v[230:231]
	v_pk_fma_f32 v[232:233], v[148:149], v[40:41], v[232:233]
	v_pk_fma_f32 v[234:235], v[152:153], v[40:41], v[234:235]
	v_pk_fma_f32 v[236:237], v[156:157], v[40:41], v[236:237]
	v_pk_fma_f32 v[238:239], v[160:161], v[40:41], v[238:239]
	v_pk_fma_f32 v[240:241], v[164:165], v[40:41], v[240:241]
	v_pk_fma_f32 v[242:243], v[168:169], v[40:41], v[242:243]
	ds_read_b128 v[134:137], v1 offset:368
	ds_read_b128 v[138:141], v1 offset:4464
	ds_read_b128 v[142:145], v1 offset:8560
	ds_read_b128 v[146:149], v1 offset:12656
	ds_read_b128 v[150:153], v1 offset:16752
	ds_read_b128 v[154:157], v1 offset:20848
	ds_read_b128 v[158:161], v1 offset:24944
	ds_read_b128 v[162:165], v1 offset:29040
	ds_read_b128 v[166:169], v1 offset:33136
	s_waitcnt lgkmcnt(9)
; #define LAS __attribute__((address_space(3)))
; __device__ __forceinline__ void prologue(const __attribute__((address_space(4))) Args& a, ldsp lds, int gw, int NGW, int wave, int lane, const int tid, const int bid, const int G) {
;     ...
;         for (int k = wave * 128; k < wave * 128 + 128; k += 16) {
;             float wv[16];
; #pragma unroll
;             for (int q = 0; q < 16; ++q) wv[q] = Wl[(size_t)(k + q) * NMOD];
; #pragma unroll
;             for (int q4 = 0; q4 < 4; ++q4)
; #pragma unroll
;                 for (int j = 0; j < 9; ++j) { const f32x4 s4 = *(const LAS f32x4*)(sc + j * D + k + 4 * q4); acc[j] += s4[0] * wv[4 * q4] + s4[1] * wv[4 * q4 + 1] + s4[2] * wv[4 * q4 + 2] + s4[3] * wv[4 * q4 + 3]; }
	v_pk_fma_f32 v[226:227], v[98:99], v[42:43], v[226:227]
	v_pk_fma_f32 v[228:229], v[102:103], v[42:43], v[228:229]
	v_pk_fma_f32 v[230:231], v[106:107], v[42:43], v[230:231]
	v_pk_fma_f32 v[232:233], v[110:111], v[42:43], v[232:233]
	v_pk_fma_f32 v[234:235], v[114:115], v[42:43], v[234:235]
	v_pk_fma_f32 v[236:237], v[118:119], v[42:43], v[236:237]
	v_pk_fma_f32 v[238:239], v[122:123], v[42:43], v[238:239]
	v_pk_fma_f32 v[240:241], v[126:127], v[42:43], v[240:241]
	v_pk_fma_f32 v[242:243], v[130:131], v[42:43], v[242:243]
	v_pk_fma_f32 v[226:227], v[100:101], v[44:45], v[226:227]
	v_pk_fma_f32 v[228:229], v[104:105], v[44:45], v[228:229]
	v_pk_fma_f32 v[230:231], v[108:109], v[44:45], v[230:231]
	v_pk_fma_f32 v[232:233], v[112:113], v[44:45], v[232:233]
	v_pk_fma_f32 v[234:235], v[116:117], v[44:45], v[234:235]
	v_pk_fma_f32 v[236:237], v[120:121], v[44:45], v[236:237]
	v_pk_fma_f32 v[238:239], v[124:125], v[44:45], v[238:239]
	v_pk_fma_f32 v[240:241], v[128:129], v[44:45], v[240:241]
	v_pk_fma_f32 v[242:243], v[132:133], v[44:45], v[242:243]
	ds_read_b128 v[98:101], v1 offset:384
	ds_read_b128 v[102:105], v1 offset:4480
	ds_read_b128 v[106:109], v1 offset:8576
	ds_read_b128 v[110:113], v1 offset:12672
	ds_read_b128 v[114:117], v1 offset:16768
	ds_read_b128 v[118:121], v1 offset:20864
	ds_read_b128 v[122:125], v1 offset:24960
	ds_read_b128 v[126:129], v1 offset:29056
	ds_read_b128 v[130:133], v1 offset:33152
	s_waitcnt lgkmcnt(9)
	v_pk_fma_f32 v[226:227], v[134:135], v[46:47], v[226:227]
	v_pk_fma_f32 v[228:229], v[138:139], v[46:47], v[228:229]
	v_pk_fma_f32 v[230:231], v[142:143], v[46:47], v[230:231]
	v_pk_fma_f32 v[232:233], v[146:147], v[46:47], v[232:233]
	v_pk_fma_f32 v[234:235], v[150:151], v[46:47], v[234:235]
	v_pk_fma_f32 v[236:237], v[154:155], v[46:47], v[236:237]
	v_pk_fma_f32 v[238:239], v[158:159], v[46:47], v[238:239]
	v_pk_fma_f32 v[240:241], v[162:163], v[46:47], v[240:241]
	v_pk_fma_f32 v[242:243], v[166:167], v[46:47], v[242:243]
	v_pk_fma_f32 v[226:227], v[136:137], v[48:49], v[226:227]
	v_pk_fma_f32 v[228:229], v[140:141], v[48:49], v[228:229]
	v_pk_fma_f32 v[230:231], v[144:145], v[48:49], v[230:231]
	v_pk_fma_f32 v[232:233], v[148:149], v[48:49], v[232:233]
	v_pk_fma_f32 v[234:235], v[152:153], v[48:49], v[234:235]
	v_pk_fma_f32 v[236:237], v[156:157], v[48:49], v[236:237]
	v_pk_fma_f32 v[238:239], v[160:161], v[48:49], v[238:239]
	v_pk_fma_f32 v[240:241], v[164:165], v[48:49], v[240:241]
	v_pk_fma_f32 v[242:243], v[168:169], v[48:49], v[242:243]
	global_load_dword v34, v0, s[22:23] nt
	s_add_u32 s22, s22, 0x6000
	s_addc_u32 s23, s23, 0
	global_load_dword v35, v0, s[22:23] nt
	s_add_u32 s22, s22, 0x6000
	s_addc_u32 s23, s23, 0
	global_load_dword v36, v0, s[22:23] nt
	s_add_u32 s22, s22, 0x6000
	s_addc_u32 s23, s23, 0
	global_load_dword v37, v0, s[22:23] nt
	s_add_u32 s22, s22, 0x6000
	s_addc_u32 s23, s23, 0
	global_load_dword v38, v0, s[22:23] nt
	s_add_u32 s22, s22, 0x6000
	s_addc_u32 s23, s23, 0
	global_load_dword v39, v0, s[22:23] nt
	s_add_u32 s22, s22, 0x6000
	s_addc_u32 s23, s23, 0
	global_load_dword v40, v0, s[22:23] nt
	s_add_u32 s22, s22, 0x6000
	s_addc_u32 s23, s23, 0
	global_load_dword v41, v0, s[22:23] nt
	s_add_u32 s22, s22, 0x6000
	s_addc_u32 s23, s23, 0
	global_load_dword v42, v0, s[22:23] nt
	s_add_u32 s22, s22, 0x6000
	s_addc_u32 s23, s23, 0
	global_load_dword v43, v0, s[22:23] nt
	s_add_u32 s22, s22, 0x6000
	s_addc_u32 s23, s23, 0
	global_load_dword v44, v0, s[22:23] nt
	s_add_u32 s22, s22, 0x6000
	s_addc_u32 s23, s23, 0
	global_load_dword v45, v0, s[22:23] nt
	s_add_u32 s22, s22, 0x6000
	s_addc_u32 s23, s23, 0
	global_load_dword v46, v0, s[22:23] nt
	s_add_u32 s22, s22, 0x6000
	s_addc_u32 s23, s23, 0
	global_load_dword v47, v0, s[22:23] nt
	s_add_u32 s22, s22, 0x6000
	s_addc_u32 s23, s23, 0
	global_load_dword v48, v0, s[22:23] nt
	s_add_u32 s22, s22, 0x6000
	s_addc_u32 s23, s23, 0
	global_load_dword v49, v0, s[22:23] nt
	s_add_u32 s22, s22, 0x6000
	s_addc_u32 s23, s23, 0
	s_waitcnt vmcnt(16)
	ds_read_b128 v[134:137], v1 offset:400
	ds_read_b128 v[138:141], v1 offset:4496
	ds_read_b128 v[142:145], v1 offset:8592
	ds_read_b128 v[146:149], v1 offset:12688
	ds_read_b128 v[150:153], v1 offset:16784
	ds_read_b128 v[154:157], v1 offset:20880
	ds_read_b128 v[158:161], v1 offset:24976
	ds_read_b128 v[162:165], v1 offset:29072
	ds_read_b128 v[166:169], v1 offset:33168
	s_waitcnt lgkmcnt(9)
	v_pk_fma_f32 v[226:227], v[98:99], v[2:3], v[226:227]
	v_pk_fma_f32 v[228:229], v[102:103], v[2:3], v[228:229]
	v_pk_fma_f32 v[230:231], v[106:107], v[2:3], v[230:231]
	v_pk_fma_f32 v[232:233], v[110:111], v[2:3], v[232:233]
	v_pk_fma_f32 v[234:235], v[114:115], v[2:3], v[234:235]
	v_pk_fma_f32 v[236:237], v[118:119], v[2:3], v[236:237]
	v_pk_fma_f32 v[238:239], v[122:123], v[2:3], v[238:239]
	v_pk_fma_f32 v[240:241], v[126:127], v[2:3], v[240:241]
	v_pk_fma_f32 v[242:243], v[130:131], v[2:3], v[242:243]
	v_pk_fma_f32 v[226:227], v[100:101], v[4:5], v[226:227]
	v_pk_fma_f32 v[228:229], v[104:105], v[4:5], v[228:229]
	v_pk_fma_f32 v[230:231], v[108:109], v[4:5], v[230:231]
	v_pk_fma_f32 v[232:233], v[112:113], v[4:5], v[232:233]
	v_pk_fma_f32 v[234:235], v[116:117], v[4:5], v[234:235]
	v_pk_fma_f32 v[236:237], v[120:121], v[4:5], v[236:237]
	v_pk_fma_f32 v[238:239], v[124:125], v[4:5], v[238:239]
	v_pk_fma_f32 v[240:241], v[128:129], v[4:5], v[240:241]
	v_pk_fma_f32 v[242:243], v[132:133], v[4:5], v[242:243]
	ds_read_b128 v[98:101], v1 offset:416
	ds_read_b128 v[102:105], v1 offset:4512
	ds_read_b128 v[106:109], v1 offset:8608
	ds_read_b128 v[110:113], v1 offset:12704
	ds_read_b128 v[114:117], v1 offset:16800
	ds_read_b128 v[118:121], v1 offset:20896
	ds_read_b128 v[122:125], v1 offset:24992
	ds_read_b128 v[126:129], v1 offset:29088
	ds_read_b128 v[130:133], v1 offset:33184
	s_waitcnt lgkmcnt(9)
; #define LAS __attribute__((address_space(3)))
; __device__ __forceinline__ void prologue(const __attribute__((address_space(4))) Args& a, ldsp lds, int gw, int NGW, int wave, int lane, const int tid, const int bid, const int G) {
;     ...
; #pragma unroll
;             for (int q4 = 0; q4 < 4; ++q4)
; #pragma unroll
;                 for (int j = 0; j < 9; ++j) { const f32x4 s4 = *(const LAS f32x4*)(sc + j * D + k + 4 * q4); acc[j] += s4[0] * wv[4 * q4] + s4[1] * wv[4 * q4 + 1] + s4[2] * wv[4 * q4 + 2] + s4[3] * wv[4 * q4 + 3]; }
	v_pk_fma_f32 v[226:227], v[134:135], v[6:7], v[226:227]
	v_pk_fma_f32 v[228:229], v[138:139], v[6:7], v[228:229]
	v_pk_fma_f32 v[230:231], v[142:143], v[6:7], v[230:231]
	v_pk_fma_f32 v[232:233], v[146:147], v[6:7], v[232:233]
	v_pk_fma_f32 v[234:235], v[150:151], v[6:7], v[234:235]
	v_pk_fma_f32 v[236:237], v[154:155], v[6:7], v[236:237]
	v_pk_fma_f32 v[238:239], v[158:159], v[6:7], v[238:239]
	v_pk_fma_f32 v[240:241], v[162:163], v[6:7], v[240:241]
	v_pk_fma_f32 v[242:243], v[166:167], v[6:7], v[242:243]
	v_pk_fma_f32 v[226:227], v[136:137], v[8:9], v[226:227]
	v_pk_fma_f32 v[228:229], v[140:141], v[8:9], v[228:229]
	v_pk_fma_f32 v[230:231], v[144:145], v[8:9], v[230:231]
	v_pk_fma_f32 v[232:233], v[148:149], v[8:9], v[232:233]
	v_pk_fma_f32 v[234:235], v[152:153], v[8:9], v[234:235]
	v_pk_fma_f32 v[236:237], v[156:157], v[8:9], v[236:237]
	v_pk_fma_f32 v[238:239], v[160:161], v[8:9], v[238:239]
	v_pk_fma_f32 v[240:241], v[164:165], v[8:9], v[240:241]
	v_pk_fma_f32 v[242:243], v[168:169], v[8:9], v[242:243]
	ds_read_b128 v[134:137], v1 offset:432
	ds_read_b128 v[138:141], v1 offset:4528
	ds_read_b128 v[142:145], v1 offset:8624
	ds_read_b128 v[146:149], v1 offset:12720
	ds_read_b128 v[150:153], v1 offset:16816
	ds_read_b128 v[154:157], v1 offset:20912
	ds_read_b128 v[158:161], v1 offset:25008
	ds_read_b128 v[162:165], v1 offset:29104
	ds_read_b128 v[166:169], v1 offset:33200
	s_waitcnt lgkmcnt(9)
	v_pk_fma_f32 v[226:227], v[98:99], v[10:11], v[226:227]
	v_pk_fma_f32 v[228:229], v[102:103], v[10:11], v[228:229]
	v_pk_fma_f32 v[230:231], v[106:107], v[10:11], v[230:231]
	v_pk_fma_f32 v[232:233], v[110:111], v[10:11], v[232:233]
	v_pk_fma_f32 v[234:235], v[114:115], v[10:11], v[234:235]
	v_pk_fma_f32 v[236:237], v[118:119], v[10:11], v[236:237]
	v_pk_fma_f32 v[238:239], v[122:123], v[10:11], v[238:239]
	v_pk_fma_f32 v[240:241], v[126:127], v[10:11], v[240:241]
	v_pk_fma_f32 v[242:243], v[130:131], v[10:11], v[242:243]
	v_pk_fma_f32 v[226:227], v[100:101], v[12:13], v[226:227]
	v_pk_fma_f32 v[228:229], v[104:105], v[12:13], v[228:229]
	v_pk_fma_f32 v[230:231], v[108:109], v[12:13], v[230:231]
	v_pk_fma_f32 v[232:233], v[112:113], v[12:13], v[232:233]
	v_pk_fma_f32 v[234:235], v[116:117], v[12:13], v[234:235]
	v_pk_fma_f32 v[236:237], v[120:121], v[12:13], v[236:237]
	v_pk_fma_f32 v[238:239], v[124:125], v[12:13], v[238:239]
	v_pk_fma_f32 v[240:241], v[128:129], v[12:13], v[240:241]
	v_pk_fma_f32 v[242:243], v[132:133], v[12:13], v[242:243]
	ds_read_b128 v[98:101], v1 offset:448
	ds_read_b128 v[102:105], v1 offset:4544
	ds_read_b128 v[106:109], v1 offset:8640
	ds_read_b128 v[110:113], v1 offset:12736
	ds_read_b128 v[114:117], v1 offset:16832
	ds_read_b128 v[118:121], v1 offset:20928
	ds_read_b128 v[122:125], v1 offset:25024
	ds_read_b128 v[126:129], v1 offset:29120
	ds_read_b128 v[130:133], v1 offset:33216
	s_waitcnt lgkmcnt(9)
	v_pk_fma_f32 v[226:227], v[134:135], v[14:15], v[226:227]
	v_pk_fma_f32 v[228:229], v[138:139], v[14:15], v[228:229]
	v_pk_fma_f32 v[230:231], v[142:143], v[14:15], v[230:231]
	v_pk_fma_f32 v[232:233], v[146:147], v[14:15], v[232:233]
	v_pk_fma_f32 v[234:235], v[150:151], v[14:15], v[234:235]
	v_pk_fma_f32 v[236:237], v[154:155], v[14:15], v[236:237]
	v_pk_fma_f32 v[238:239], v[158:159], v[14:15], v[238:239]
	v_pk_fma_f32 v[240:241], v[162:163], v[14:15], v[240:241]
	v_pk_fma_f32 v[242:243], v[166:167], v[14:15], v[242:243]
	v_pk_fma_f32 v[226:227], v[136:137], v[16:17], v[226:227]
	v_pk_fma_f32 v[228:229], v[140:141], v[16:17], v[228:229]
	v_pk_fma_f32 v[230:231], v[144:145], v[16:17], v[230:231]
	v_pk_fma_f32 v[232:233], v[148:149], v[16:17], v[232:233]
	v_pk_fma_f32 v[234:235], v[152:153], v[16:17], v[234:235]
	v_pk_fma_f32 v[236:237], v[156:157], v[16:17], v[236:237]
	v_pk_fma_f32 v[238:239], v[160:161], v[16:17], v[238:239]
	v_pk_fma_f32 v[240:241], v[164:165], v[16:17], v[240:241]
	v_pk_fma_f32 v[242:243], v[168:169], v[16:17], v[242:243]
	s_waitcnt vmcnt(0)
	ds_read_b128 v[134:137], v1 offset:464
	ds_read_b128 v[138:141], v1 offset:4560
	ds_read_b128 v[142:145], v1 offset:8656
	ds_read_b128 v[146:149], v1 offset:12752
	ds_read_b128 v[150:153], v1 offset:16848
	ds_read_b128 v[154:157], v1 offset:20944
	ds_read_b128 v[158:161], v1 offset:25040
	ds_read_b128 v[162:165], v1 offset:29136
	ds_read_b128 v[166:169], v1 offset:33232
	s_waitcnt lgkmcnt(9)
	v_pk_fma_f32 v[226:227], v[98:99], v[34:35], v[226:227]
	v_pk_fma_f32 v[228:229], v[102:103], v[34:35], v[228:229]
	v_pk_fma_f32 v[230:231], v[106:107], v[34:35], v[230:231]
	v_pk_fma_f32 v[232:233], v[110:111], v[34:35], v[232:233]
	v_pk_fma_f32 v[234:235], v[114:115], v[34:35], v[234:235]
	v_pk_fma_f32 v[236:237], v[118:119], v[34:35], v[236:237]
	v_pk_fma_f32 v[238:239], v[122:123], v[34:35], v[238:239]
	v_pk_fma_f32 v[240:241], v[126:127], v[34:35], v[240:241]
	v_pk_fma_f32 v[242:243], v[130:131], v[34:35], v[242:243]
	v_pk_fma_f32 v[226:227], v[100:101], v[36:37], v[226:227]
	v_pk_fma_f32 v[228:229], v[104:105], v[36:37], v[228:229]
	v_pk_fma_f32 v[230:231], v[108:109], v[36:37], v[230:231]
	v_pk_fma_f32 v[232:233], v[112:113], v[36:37], v[232:233]
	v_pk_fma_f32 v[234:235], v[116:117], v[36:37], v[234:235]
	v_pk_fma_f32 v[236:237], v[120:121], v[36:37], v[236:237]
	v_pk_fma_f32 v[238:239], v[124:125], v[36:37], v[238:239]
	v_pk_fma_f32 v[240:241], v[128:129], v[36:37], v[240:241]
	v_pk_fma_f32 v[242:243], v[132:133], v[36:37], v[242:243]
	ds_read_b128 v[98:101], v1 offset:480
	ds_read_b128 v[102:105], v1 offset:4576
	ds_read_b128 v[106:109], v1 offset:8672
	ds_read_b128 v[110:113], v1 offset:12768
	ds_read_b128 v[114:117], v1 offset:16864
	ds_read_b128 v[118:121], v1 offset:20960
	ds_read_b128 v[122:125], v1 offset:25056
	ds_read_b128 v[126:129], v1 offset:29152
	ds_read_b128 v[130:133], v1 offset:33248
	s_waitcnt lgkmcnt(9)
; #define LAS __attribute__((address_space(3)))
; __device__ __forceinline__ void prologue(const __attribute__((address_space(4))) Args& a, ldsp lds, int gw, int NGW, int wave, int lane, const int tid, const int bid, const int G) {
;     ...
; #pragma unroll
;             for (int q4 = 0; q4 < 4; ++q4)
; #pragma unroll
;                 for (int j = 0; j < 9; ++j) { const f32x4 s4 = *(const LAS f32x4*)(sc + j * D + k + 4 * q4); acc[j] += s4[0] * wv[4 * q4] + s4[1] * wv[4 * q4 + 1] + s4[2] * wv[4 * q4 + 2] + s4[3] * wv[4 * q4 + 3]; }
;         }
; #pragma unroll
;         for (int j = 0; j < 9; ++j) red[(wave * 9 + j) * 64 + lane] = acc[j];
;         __syncthreads();
;         for (int i = tid; i < 9 * 64; i += 512) { const int j = i >> 6, cc = i & 63; float s = a.ada_b[layer * NMOD + col0 + cc];
; #pragma unroll
;             for (int w = 0; w < 8; ++w) s += red[(w * 9 + j) * 64 + cc];
;             mods[((size_t)layer * 9 + j) * NMOD + col0 + cc] = s; }
	v_pk_fma_f32 v[226:227], v[134:135], v[38:39], v[226:227]
	v_pk_fma_f32 v[228:229], v[138:139], v[38:39], v[228:229]
	v_pk_fma_f32 v[230:231], v[142:143], v[38:39], v[230:231]
	v_pk_fma_f32 v[232:233], v[146:147], v[38:39], v[232:233]
	v_pk_fma_f32 v[234:235], v[150:151], v[38:39], v[234:235]
	v_pk_fma_f32 v[236:237], v[154:155], v[38:39], v[236:237]
	v_pk_fma_f32 v[238:239], v[158:159], v[38:39], v[238:239]
	v_pk_fma_f32 v[240:241], v[162:163], v[38:39], v[240:241]
	v_pk_fma_f32 v[242:243], v[166:167], v[38:39], v[242:243]
	v_pk_fma_f32 v[226:227], v[136:137], v[40:41], v[226:227]
	v_pk_fma_f32 v[228:229], v[140:141], v[40:41], v[228:229]
	v_pk_fma_f32 v[230:231], v[144:145], v[40:41], v[230:231]
	v_pk_fma_f32 v[232:233], v[148:149], v[40:41], v[232:233]
	v_pk_fma_f32 v[234:235], v[152:153], v[40:41], v[234:235]
	v_pk_fma_f32 v[236:237], v[156:157], v[40:41], v[236:237]
	v_pk_fma_f32 v[238:239], v[160:161], v[40:41], v[238:239]
	v_pk_fma_f32 v[240:241], v[164:165], v[40:41], v[240:241]
	v_pk_fma_f32 v[242:243], v[168:169], v[40:41], v[242:243]
	ds_read_b128 v[134:137], v1 offset:496
	ds_read_b128 v[138:141], v1 offset:4592
	ds_read_b128 v[142:145], v1 offset:8688
	ds_read_b128 v[146:149], v1 offset:12784
	ds_read_b128 v[150:153], v1 offset:16880
	ds_read_b128 v[154:157], v1 offset:20976
	ds_read_b128 v[158:161], v1 offset:25072
	ds_read_b128 v[162:165], v1 offset:29168
	ds_read_b128 v[166:169], v1 offset:33264
	s_waitcnt lgkmcnt(9)
	v_pk_fma_f32 v[226:227], v[98:99], v[42:43], v[226:227]
	v_pk_fma_f32 v[228:229], v[102:103], v[42:43], v[228:229]
	v_pk_fma_f32 v[230:231], v[106:107], v[42:43], v[230:231]
	v_pk_fma_f32 v[232:233], v[110:111], v[42:43], v[232:233]
	v_pk_fma_f32 v[234:235], v[114:115], v[42:43], v[234:235]
	v_pk_fma_f32 v[236:237], v[118:119], v[42:43], v[236:237]
	v_pk_fma_f32 v[238:239], v[122:123], v[42:43], v[238:239]
	v_pk_fma_f32 v[240:241], v[126:127], v[42:43], v[240:241]
	v_pk_fma_f32 v[242:243], v[130:131], v[42:43], v[242:243]
	v_pk_fma_f32 v[226:227], v[100:101], v[44:45], v[226:227]
	v_pk_fma_f32 v[228:229], v[104:105], v[44:45], v[228:229]
	v_pk_fma_f32 v[230:231], v[108:109], v[44:45], v[230:231]
	v_pk_fma_f32 v[232:233], v[112:113], v[44:45], v[232:233]
	v_pk_fma_f32 v[234:235], v[116:117], v[44:45], v[234:235]
	v_pk_fma_f32 v[236:237], v[120:121], v[44:45], v[236:237]
	v_pk_fma_f32 v[238:239], v[124:125], v[44:45], v[238:239]
	v_pk_fma_f32 v[240:241], v[128:129], v[44:45], v[240:241]
	v_pk_fma_f32 v[242:243], v[132:133], v[44:45], v[242:243]
	s_waitcnt lgkmcnt(0)
	v_pk_fma_f32 v[226:227], v[134:135], v[46:47], v[226:227]
	v_pk_fma_f32 v[228:229], v[138:139], v[46:47], v[228:229]
	v_pk_fma_f32 v[230:231], v[142:143], v[46:47], v[230:231]
	v_pk_fma_f32 v[232:233], v[146:147], v[46:47], v[232:233]
	v_pk_fma_f32 v[234:235], v[150:151], v[46:47], v[234:235]
	v_pk_fma_f32 v[236:237], v[154:155], v[46:47], v[236:237]
	v_pk_fma_f32 v[238:239], v[158:159], v[46:47], v[238:239]
	v_pk_fma_f32 v[240:241], v[162:163], v[46:47], v[240:241]
	v_pk_fma_f32 v[242:243], v[166:167], v[46:47], v[242:243]
	v_pk_fma_f32 v[226:227], v[136:137], v[48:49], v[226:227]
	v_pk_fma_f32 v[228:229], v[140:141], v[48:49], v[228:229]
	v_pk_fma_f32 v[230:231], v[144:145], v[48:49], v[230:231]
	v_pk_fma_f32 v[232:233], v[148:149], v[48:49], v[232:233]
	v_pk_fma_f32 v[234:235], v[152:153], v[48:49], v[234:235]
	v_pk_fma_f32 v[236:237], v[156:157], v[48:49], v[236:237]
	v_pk_fma_f32 v[238:239], v[160:161], v[48:49], v[238:239]
	v_pk_fma_f32 v[240:241], v[164:165], v[48:49], v[240:241]
	v_pk_fma_f32 v[242:243], v[168:169], v[48:49], v[242:243]
	v_add_f32_e32 v78, v226, v227
	v_add_f32_e32 v79, v228, v229
	v_add_f32_e32 v84, v230, v231
	v_add_f32_e32 v85, v232, v233
	v_add_f32_e32 v82, v234, v235
	v_add_f32_e32 v83, v236, v237
	v_add_f32_e32 v80, v238, v239
	v_add_f32_e32 v81, v240, v241
	v_add_f32_e32 v92, v242, v243
	ds_write2st64_b32 v91, v78, v79 offset1:1
	ds_write2st64_b32 v91, v84, v85 offset0:2 offset1:3
	ds_write2st64_b32 v91, v82, v83 offset0:4 offset1:5
	ds_write2st64_b32 v91, v80, v81 offset0:6 offset1:7
	ds_write_b32 v91, v92 offset:2048
	s_waitcnt lgkmcnt(0)
	s_barrier
	s_and_saveexec_b64 s[8:9], s[4:5]
	s_cbranch_execz .LBB0_1276
	s_mul_i32 s13, s12, 0x1800
	s_add_i32 s14, s13, s6
	v_or_b32_e32 v0, s14, v87
	v_ashrrev_i32_e32 v1, 31, v0
	s_mul_hi_i32 s13, s12, 9
	s_mul_i32 s12, s12, 9
	v_lshl_add_u64 v[0:1], v[0:1], 2, s[10:11]
	v_lshl_add_u64 v[2:3], s[6:7], 2, v[72:73]
	s_mov_b64 s[6:7], 0
	v_mov_b32_e32 v4, v196
